# ALIGN_EPI barrier of the leading wave half moved into the epilogue (G4: before the gate-load wait, G3b: after 3rd store, G5: before load wait, S: after 6th store) so it overlaps the trailing half's la
# speedup vs baseline: 1.0004x; 1.0004x over previous
; #define G8_STA(bufoff, ptr, sg, h) G8_STAGE1(bufoff, (ptr) + (h) * ((sg) ? hA1 : hA0), ((sg) ? voffA1 : voffA0), ((sg) ? r64A1 : r64A0))
; #define G8_STB(bufoff, ptr, sg, h) G8_STAGE1(bufoff, (ptr) + (h) * ((sg) ? hB1 : hB0), ((sg) ? voffB1 : voffB0), ((sg) ? r64B1 : r64B0))
; #define G8_LDA(dst, b, h) do { _Pragma("unroll") for (int m = 0; m < 4; ++m) _Pragma("unroll") for (int k = 0; k < 2; ++k) dst[m][k] = *(const LAS bf16x8*)(lds + G8_SA(b, h) + aoff + m * 2048 + k * 1024); } while (0)
; #define G8_LDB(dst, b, h) do { _Pragma("unroll") for (int n = 0; n < 2; ++n) _Pragma("unroll") for (int k = 0; k < 2; ++k) dst[n][k] = *(const LAS bf16x8*)(lds + G8_SB(b, h) + boff + n * 2048 + k * 1024); } while (0)
; #define G8_MMA(ai, bj, At, Bt) do { __builtin_amdgcn_s_setprio(1); _Pragma("unroll") for (int m = 0; m < 4; ++m) _Pragma("unroll") for (int n = 0; n < 2; ++n) _Pragma("unroll") for (int k = 0; k < 2; ++k) \
;         acc[ai][bj][m][n] = __builtin_amdgcn_mfma_f32_16x16x32_bf16(Bt[n][k], At[m][k], acc[ai][bj][m][n], 0, 0, 0); __builtin_amdgcn_s_setprio(0); } while (0)
; #define G8_WAIT_V(n) asm volatile("s_waitcnt vmcnt(" #n ")" ::: "memory")
; #define G8_WAIT_L(n) asm volatile("s_waitcnt lgkmcnt(" #n ")" ::: "memory")
; #define G8_BAR __builtin_amdgcn_s_barrier()
; #define G8_SCHED __builtin_amdgcn_sched_barrier(0)
; template <class P>
; __device__ __forceinline__ void gemm_phase(LAS unsigned char* lds, const P& p, const int G, const int c) {
;     ...
;             G8_LDB(B0, 1, 0); G8_LDB(B1, 1, 1); G8_SCHED; G8_LDA(At, 1, 0); G8_STA(G8_SA(0, 1), a2, sg2, 1);
;             G8_WAIT_V(8); G8_WAIT_L(0); G8_BAR; G8_MMA(0, 0, At, B0); G8_MMA(0, 1, At, B1); G8_BAR; G8_SCHED;
;             G8_LDA(At, 1, 1); G8_STB(G8_SB(1, 0), b3, sg2, 0); G8_STB(G8_SB(1, 1), b3, sg2, 1); G8_STA(G8_SA(1, 0), a3, sg2, 0);
;             G8_WAIT_V(8); G8_WAIT_L(0); G8_BAR; G8_MMA(1, 0, At, B0); G8_MMA(1, 1, At, B1); G8_BAR; G8_SCHED;
;         }
.Lmid_539:
	s_barrier
	s_add_i32 s35, 0, 0x18000
	v_add_u32_e32 v130, s35, v156
	s_add_i32 s20, 0, 0x1c000
	ds_read_b128 v[160:163], v130
	ds_read_b128 v[164:167], v130 offset:1024
	ds_read_b128 v[168:171], v130 offset:2048
	ds_read_b128 v[172:175], v130 offset:3072
	v_add_u32_e32 v130, s20, v156
	ds_read_b128 v[176:179], v130
	ds_read_b128 v[180:183], v130 offset:1024
	ds_read_b128 v[184:187], v130 offset:2048
	ds_read_b128 v[188:191], v130 offset:3072
	s_mov_b32 m0, s15
	v_lshl_add_u64 v[230:231], v[228:229], 0, s[36:37]
	ds_read_b128 v[192:195], v158 offset:32768
	ds_read_b128 v[196:199], v158 offset:33792
	ds_read_b128 v[200:203], v158 offset:34816
	ds_read_b128 v[204:207], v158 offset:35840
	ds_read_b128 v[210:213], v158 offset:36864
	ds_read_b128 v[214:217], v158 offset:37888
	ds_read_b128 v[218:221], v158 offset:38912
	ds_read_b128 v[222:225], v158 offset:39936
	global_load_lds_dwordx4 v[230:231], off
	v_lshl_add_u64 v[230:231], v[228:229], 0, s[38:39]
	s_mov_b32 m0, s16
	s_nop 0
	global_load_lds_dwordx4 v[230:231], off
	s_waitcnt vmcnt(8)
	s_waitcnt lgkmcnt(0)
	s_barrier
	s_waitcnt lgkmcnt(0)
	v_mfma_f32_16x16x32_bf16 v[126:129], v[160:163], v[192:195], v[126:129]
	v_mfma_f32_16x16x32_bf16 v[122:125], v[168:171], v[192:195], v[122:125]
	v_mfma_f32_16x16x32_bf16 v[118:121], v[160:163], v[200:203], v[118:121]
	v_mfma_f32_16x16x32_bf16 v[114:117], v[168:171], v[200:203], v[114:117]
	v_mfma_f32_16x16x32_bf16 v[102:105], v[160:163], v[210:213], v[102:105]
	v_mfma_f32_16x16x32_bf16 v[98:101], v[168:171], v[210:213], v[98:101]
	v_mfma_f32_16x16x32_bf16 v[86:89], v[160:163], v[218:221], v[86:89]
	v_mfma_f32_16x16x32_bf16 v[82:85], v[168:171], v[218:221], v[82:85]
	v_mfma_f32_16x16x32_bf16 v[126:129], v[164:167], v[196:199], v[126:129]
	v_mfma_f32_16x16x32_bf16 v[122:125], v[172:175], v[196:199], v[122:125]
	v_mfma_f32_16x16x32_bf16 v[118:121], v[164:167], v[204:207], v[118:121]
	v_mfma_f32_16x16x32_bf16 v[114:117], v[172:175], v[204:207], v[114:117]
	v_mfma_f32_16x16x32_bf16 v[102:105], v[164:167], v[214:217], v[102:105]
	v_mfma_f32_16x16x32_bf16 v[98:101], v[172:175], v[214:217], v[98:101]
	v_mfma_f32_16x16x32_bf16 v[86:89], v[164:167], v[222:225], v[86:89]
	v_mfma_f32_16x16x32_bf16 v[82:85], v[172:175], v[222:225], v[82:85]
	v_mfma_f32_16x16x32_bf16 v[110:113], v[176:179], v[192:195], v[110:113]
	v_mfma_f32_16x16x32_bf16 v[106:109], v[184:187], v[192:195], v[106:109]
	v_mfma_f32_16x16x32_bf16 v[94:97], v[176:179], v[200:203], v[94:97]
	v_mfma_f32_16x16x32_bf16 v[90:93], v[184:187], v[200:203], v[90:93]
	v_mfma_f32_16x16x32_bf16 v[78:81], v[176:179], v[210:213], v[78:81]
	v_mfma_f32_16x16x32_bf16 v[74:77], v[184:187], v[210:213], v[74:77]
	v_mfma_f32_16x16x32_bf16 v[70:73], v[176:179], v[218:221], v[70:73]
	v_mfma_f32_16x16x32_bf16 v[66:69], v[184:187], v[218:221], v[66:69]
	v_mfma_f32_16x16x32_bf16 v[110:113], v[180:183], v[196:199], v[110:113]
	v_mfma_f32_16x16x32_bf16 v[106:109], v[188:191], v[196:199], v[106:109]
	v_mfma_f32_16x16x32_bf16 v[94:97], v[180:183], v[204:207], v[94:97]
	v_mfma_f32_16x16x32_bf16 v[90:93], v[188:191], v[204:207], v[90:93]
	v_mfma_f32_16x16x32_bf16 v[78:81], v[180:183], v[214:217], v[78:81]
	v_mfma_f32_16x16x32_bf16 v[74:77], v[188:191], v[214:217], v[74:77]
	v_mfma_f32_16x16x32_bf16 v[70:73], v[180:183], v[222:225], v[70:73]
	v_mfma_f32_16x16x32_bf16 v[66:69], v[188:191], v[222:225], v[66:69]
	s_barrier
	s_add_i32 s6, s35, s10
	v_lshl_add_u64 v[230:231], v[226:227], 0, s[40:41]
	s_mov_b32 m0, s6
	ds_read_b128 v[192:195], v158 offset:49152
	ds_read_b128 v[196:199], v158 offset:50176
	ds_read_b128 v[200:203], v158 offset:51200
	ds_read_b128 v[204:207], v158 offset:52224
	ds_read_b128 v[210:213], v158 offset:53248
	ds_read_b128 v[214:217], v158 offset:54272
	ds_read_b128 v[218:221], v158 offset:55296
	ds_read_b128 v[222:225], v158 offset:56320
	global_load_lds_dwordx4 v[230:231], off
	v_lshl_add_u64 v[230:231], v[226:227], 0, s[42:43]
	s_add_i32 m0, s6, 0x2000
	s_add_i32 s6, s20, s10
	global_load_lds_dwordx4 v[230:231], off
	v_lshl_add_u64 v[230:231], v[226:227], 0, s[48:49]
	s_mov_b32 m0, s6
	v_lshl_add_u64 v[226:227], v[226:227], 0, s[52:53]
	global_load_lds_dwordx4 v[230:231], off
	s_add_i32 m0, s6, 0x2000
	s_nop 0
	global_load_lds_dwordx4 v[226:227], off
	v_lshl_add_u64 v[226:227], v[228:229], 0, s[8:9]
	s_mov_b32 m0, s24
	s_nop 0
	global_load_lds_dwordx4 v[226:227], off
	v_lshl_add_u64 v[226:227], v[228:229], 0, s[44:45]
	s_mov_b32 m0, s25
	s_nop 0
	global_load_lds_dwordx4 v[226:227], off
	s_waitcnt vmcnt(8)
	s_waitcnt lgkmcnt(0)
	s_barrier
	s_waitcnt lgkmcnt(0)
	v_mfma_f32_16x16x32_bf16 v[62:65], v[160:163], v[192:195], v[62:65]
	v_mfma_f32_16x16x32_bf16 v[58:61], v[168:171], v[192:195], v[58:61]
	v_mfma_f32_16x16x32_bf16 v[54:57], v[160:163], v[200:203], v[54:57]
	v_mfma_f32_16x16x32_bf16 v[50:53], v[168:171], v[200:203], v[50:53]
	s_add_i32 s47, s47, 2
	v_mfma_f32_16x16x32_bf16 v[38:41], v[160:163], v[210:213], v[38:41]
	s_add_u32 s28, s28, 0x40000
	v_mfma_f32_16x16x32_bf16 v[34:37], v[168:171], v[210:213], v[34:37]
	s_addc_u32 s29, s29, 0
	v_mfma_f32_16x16x32_bf16 v[22:25], v[160:163], v[218:221], v[22:25]
	s_add_u32 s94, s94, 0x10000
	v_mfma_f32_16x16x32_bf16 v[18:21], v[168:171], v[218:221], v[18:21]
	s_addc_u32 s95, s95, 0
	v_mfma_f32_16x16x32_bf16 v[62:65], v[164:167], v[196:199], v[62:65]
	s_cmp_gt_u32 s47, 5
	v_mfma_f32_16x16x32_bf16 v[58:61], v[172:175], v[196:199], v[58:61]
	v_mfma_f32_16x16x32_bf16 v[54:57], v[164:167], v[204:207], v[54:57]
	v_mfma_f32_16x16x32_bf16 v[50:53], v[172:175], v[204:207], v[50:53]
	v_mfma_f32_16x16x32_bf16 v[38:41], v[164:167], v[214:217], v[38:41]
	v_mfma_f32_16x16x32_bf16 v[34:37], v[172:175], v[214:217], v[34:37]
	v_mfma_f32_16x16x32_bf16 v[22:25], v[164:167], v[222:225], v[22:25]
	v_mfma_f32_16x16x32_bf16 v[18:21], v[172:175], v[222:225], v[18:21]
	v_mfma_f32_16x16x32_bf16 v[46:49], v[176:179], v[192:195], v[46:49]
	v_mfma_f32_16x16x32_bf16 v[42:45], v[184:187], v[192:195], v[42:45]
	v_mfma_f32_16x16x32_bf16 v[30:33], v[176:179], v[200:203], v[30:33]
	v_mfma_f32_16x16x32_bf16 v[26:29], v[184:187], v[200:203], v[26:29]
	v_mfma_f32_16x16x32_bf16 v[14:17], v[176:179], v[210:213], v[14:17]
	v_mfma_f32_16x16x32_bf16 v[10:13], v[184:187], v[210:213], v[10:13]
	v_mfma_f32_16x16x32_bf16 v[6:9], v[176:179], v[218:221], v[6:9]
	v_mfma_f32_16x16x32_bf16 v[2:5], v[184:187], v[218:221], v[2:5]
	v_mfma_f32_16x16x32_bf16 v[46:49], v[180:183], v[196:199], v[46:49]
	v_mfma_f32_16x16x32_bf16 v[42:45], v[188:191], v[196:199], v[42:45]
	v_mfma_f32_16x16x32_bf16 v[30:33], v[180:183], v[204:207], v[30:33]
	v_mfma_f32_16x16x32_bf16 v[26:29], v[188:191], v[204:207], v[26:29]
	v_mfma_f32_16x16x32_bf16 v[14:17], v[180:183], v[214:217], v[14:17]
	v_mfma_f32_16x16x32_bf16 v[10:13], v[188:191], v[214:217], v[10:13]
	v_mfma_f32_16x16x32_bf16 v[6:9], v[180:183], v[222:225], v[6:9]
	v_mfma_f32_16x16x32_bf16 v[2:5], v[188:191], v[222:225], v[2:5]
	s_barrier
	s_cbranch_scc0 .LBB0_539
; #define LAS __attribute__((address_space(3)))
; #define G8_BAR __builtin_amdgcn_s_barrier()
; template <class P>
; __device__ __forceinline__ void gemm_phase(LAS unsigned char* lds, const P& p, const int G, const int c) {
;     ...
;         if (wr == 0) G8_BAR;
;         p.epi(acc, cur, wr, wc, fr, fq, lds);
;         if (!has_next) break;
;     __device__ __forceinline__ void epi(Acc& acc, const Unit& u, int wr, int wc, int fr, int fq, LAS unsigned char*) const {
; #pragma unroll
;         for (int ai = 0; ai < 2; ++ai)
; #pragma unroll
;             for (int m = 0; m < 4; ++m) { const int j = ai * 128 + wr * 64 + m * 16 + fr;
;                 char* rowp = S + (size_t)u.g * MiB + ((size_t)((u.pn * 256 + wc * 32 + 8 * fq) >> 3) * 256 + j) * 16;
; #pragma unroll
;                 for (int bj = 0; bj < 2; ++bj) { const f32x4 v0 = acc[ai][bj][m][0], v1 = acc[ai][bj][m][1];
;                     u32x4 w; w.x = pk2(v0[0], v0[1]); w.y = pk2(v0[2], v0[3]); w.z = pk2(v1[0], v1[1]); w.w = pk2(v1[2], v1[3]);
;                     *(u32x4*)(rowp + bj * (16 * 256 * 16)) = w; } }
;     }
.LBB0_542:
	v_lshl_or_b32 v130, s46, 8, v157
	v_lshrrev_b32_e32 v130, 3, v130
	v_lshlrev_b64 v[154:155], 12, v[130:131]
	v_lshl_add_u64 v[154:155], s[80:81], 0, v[154:155]
	v_lshl_add_u64 v[160:161], v[154:155], 0, v[136:137]
	v_cvt_pk_bf16_f32 v110, v110, v111
	v_cvt_pk_bf16_f32 v111, v112, v113
	v_cvt_pk_bf16_f32 v112, v106, v107
	v_add_co_u32_e32 v106, vcc, s21, v160
	v_cvt_pk_bf16_f32 v113, v108, v109
	s_nop 0
	v_addc_co_u32_e32 v107, vcc, 0, v161, vcc
	global_store_dwordx4 v[106:107], v[110:113], off
	v_cvt_pk_bf16_f32 v94, v94, v95
	v_cvt_pk_bf16_f32 v95, v96, v97
	v_lshl_add_u64 v[110:111], v[154:155], 0, v[138:139]
	v_cvt_pk_bf16_f32 v96, v90, v91
	v_add_co_u32_e32 v90, vcc, s21, v110
	v_cvt_pk_bf16_f32 v97, v92, v93
	s_nop 0
	v_addc_co_u32_e32 v91, vcc, 0, v111, vcc
	global_store_dwordx4 v[90:91], v[94:97], off
	v_cvt_pk_bf16_f32 v78, v78, v79
	v_cvt_pk_bf16_f32 v79, v80, v81
	v_lshl_add_u64 v[94:95], v[154:155], 0, v[140:141]
	v_cvt_pk_bf16_f32 v80, v74, v75
	v_add_co_u32_e32 v74, vcc, s21, v94
	v_cvt_pk_bf16_f32 v81, v76, v77
	s_nop 0
	v_addc_co_u32_e32 v75, vcc, 0, v95, vcc
	global_store_dwordx4 v[74:75], v[78:81], off
	v_cvt_pk_bf16_f32 v70, v70, v71
	v_cvt_pk_bf16_f32 v71, v72, v73
	v_lshl_add_u64 v[78:79], v[154:155], 0, v[142:143]
	v_cvt_pk_bf16_f32 v72, v66, v67
	v_add_co_u32_e32 v66, vcc, s21, v78
	v_cvt_pk_bf16_f32 v73, v68, v69
	s_nop 0
	v_addc_co_u32_e32 v67, vcc, 0, v79, vcc
	global_store_dwordx4 v[66:67], v[70:73], off
	v_lshl_add_u64 v[66:67], v[154:155], 0, v[144:145]
	v_cvt_pk_bf16_f32 v46, v46, v47
	v_cvt_pk_bf16_f32 v47, v48, v49
	v_cvt_pk_bf16_f32 v48, v42, v43
	v_add_co_u32_e32 v42, vcc, s21, v66
	v_cvt_pk_bf16_f32 v49, v44, v45
	s_nop 0
	v_addc_co_u32_e32 v43, vcc, 0, v67, vcc
	global_store_dwordx4 v[42:43], v[46:49], off
	v_cvt_pk_bf16_f32 v30, v30, v31
	v_cvt_pk_bf16_f32 v31, v32, v33
	v_lshl_add_u64 v[46:47], v[154:155], 0, v[146:147]
	v_cvt_pk_bf16_f32 v32, v26, v27
	v_add_co_u32_e32 v26, vcc, s21, v46
	v_cvt_pk_bf16_f32 v33, v28, v29
	s_nop 0
	v_addc_co_u32_e32 v27, vcc, 0, v47, vcc
	global_store_dwordx4 v[26:27], v[30:33], off
	s_cmp_lg_u64 s[86:87], 0
	s_cbranch_scc0 .Lalg_542
	s_barrier
.Lalg_542:
	v_cvt_pk_bf16_f32 v14, v14, v15
	v_cvt_pk_bf16_f32 v15, v16, v17
	v_lshl_add_u64 v[30:31], v[154:155], 0, v[148:149]
	v_cvt_pk_bf16_f32 v16, v10, v11
	v_add_co_u32_e32 v10, vcc, s21, v30
	v_cvt_pk_bf16_f32 v17, v12, v13
	s_nop 0
	v_addc_co_u32_e32 v11, vcc, 0, v31, vcc
	global_store_dwordx4 v[10:11], v[14:17], off
	v_cvt_pk_bf16_f32 v6, v6, v7
	v_cvt_pk_bf16_f32 v7, v8, v9
	v_lshl_add_u64 v[14:15], v[154:155], 0, v[150:151]
	v_cvt_pk_bf16_f32 v8, v2, v3
	v_add_co_u32_e32 v2, vcc, 0x10000, v14
	v_cvt_pk_bf16_f32 v126, v126, v127
	s_nop 0
	v_addc_co_u32_e32 v3, vcc, 0, v15, vcc
	v_cvt_pk_bf16_f32 v127, v128, v129
	v_cvt_pk_bf16_f32 v128, v122, v123
	v_cvt_pk_bf16_f32 v129, v124, v125
	v_cvt_pk_bf16_f32 v106, v118, v119
	v_cvt_pk_bf16_f32 v107, v120, v121
	v_cvt_pk_bf16_f32 v108, v114, v115
	v_cvt_pk_bf16_f32 v109, v116, v117
	v_cvt_pk_bf16_f32 v90, v102, v103
	v_cvt_pk_bf16_f32 v91, v104, v105
	v_cvt_pk_bf16_f32 v92, v98, v99
	v_cvt_pk_bf16_f32 v93, v100, v101
	v_cvt_pk_bf16_f32 v74, v86, v87
	v_cvt_pk_bf16_f32 v75, v88, v89
	v_cvt_pk_bf16_f32 v76, v82, v83
	v_cvt_pk_bf16_f32 v77, v84, v85
	v_cvt_pk_bf16_f32 v62, v62, v63
	v_cvt_pk_bf16_f32 v63, v64, v65
	v_cvt_pk_bf16_f32 v64, v58, v59
	v_cvt_pk_bf16_f32 v65, v60, v61
	v_cvt_pk_bf16_f32 v42, v54, v55
	v_cvt_pk_bf16_f32 v43, v56, v57
	v_cvt_pk_bf16_f32 v44, v50, v51
	v_cvt_pk_bf16_f32 v45, v52, v53
	v_cvt_pk_bf16_f32 v26, v38, v39
	v_cvt_pk_bf16_f32 v27, v40, v41
	v_cvt_pk_bf16_f32 v28, v34, v35
	v_cvt_pk_bf16_f32 v29, v36, v37
	v_cvt_pk_bf16_f32 v10, v22, v23
	v_cvt_pk_bf16_f32 v11, v24, v25
	v_cvt_pk_bf16_f32 v12, v18, v19
	v_cvt_pk_bf16_f32 v13, v20, v21
	v_cvt_pk_bf16_f32 v9, v4, v5
	s_and_b64 vcc, exec, s[4:5]
	s_mov_b64 s[4:5], -1
	global_store_dwordx4 v[160:161], v[126:129], off
	global_store_dwordx4 v[110:111], v[106:109], off
	global_store_dwordx4 v[94:95], v[90:93], off
	global_store_dwordx4 v[78:79], v[74:77], off
	global_store_dwordx4 v[66:67], v[62:65], off
	global_store_dwordx4 v[46:47], v[42:45], off
	global_store_dwordx4 v[30:31], v[26:29], off
	global_store_dwordx4 v[14:15], v[10:13], off
	global_store_dwordx4 v[2:3], v[6:9], off
	s_cbranch_vccnz .LBB0_535
	s_andn2_b64 vcc, exec, s[84:85]
	s_cbranch_vccnz .LBB0_534
	s_barrier
	s_branch .LBB0_534

; #define LAS __attribute__((address_space(3)))
; __device__ __forceinline__ f32x4 silu4(f32x4 x) { return x * sigmoid4(x); }
; #define G8_BAR __builtin_amdgcn_s_barrier()
; template <class P>
; __device__ __forceinline__ void gemm_phase(LAS unsigned char* lds, const P& p, const int G, const int c) {
;     ...
;         if (wr == 0) G8_BAR;
;     __device__ __forceinline__ void epi(Acc& acc, const Unit& u, int wr, int wc, int fr, int fq, LAS unsigned char*) const {
; #pragma unroll
;         for (int ai = 0; ai < 2; ++ai)
; #pragma unroll
;             for (int m = 0; m < 4; ++m) { const int tok = u.pm * 256 + ai * 128 + wr * 64 + m * 16 + fr;
; #pragma unroll
;                 for (int bj = 0; bj < 2; ++bj) { const int n0 = u.pn * 256 + bj * 128 + wc * 32 + 8 * fq;
;                     f32x4 v0 = acc[ai][bj][m][0], v1 = acc[ai][bj][m][1];
;                     if (u.pm >= 128) { float* rp = ucs + ((((size_t)(n0 >> 4) * 4 + u.ks) * RC + (tok - RL)) * 16) + (n0 & 15); *(f32x4*)rp = v0; *(f32x4*)(rp + 4) = v1; continue; }
;                     if (zhalf) { v0 = silu4(v0); v1 = silu4(v1); }
;                     u32x4 w; w.x = pk2(v0[0], v0[1]); w.y = pk2(v0[2], v0[3]); w.z = pk2(v1[0], v1[1]); w.w = pk2(v1[2], v1[3]);
;                     if (zhalf) *(u32x4*)(SZ + ((((size_t)(u.pm * 8 + u.pn) * 256 + (tok & 255)) * 256) + (n0 & 255)) * 2) = w;
.LBB0_682:
.LBB0_684:
	v_pk_mul_f32 v[168:169], v[128:129], s[44:45] op_sel_hi:[1,0]
	v_pk_mul_f32 v[170:171], v[126:127], s[44:45] op_sel_hi:[1,0]
	v_exp_f32_e32 v168, v168
	v_exp_f32_e32 v170, v170
	v_exp_f32_e32 v169, v169
	v_exp_f32_e32 v171, v171
	v_pk_mul_f32 v[172:173], v[124:125], s[44:45] op_sel_hi:[1,0]
	v_pk_mul_f32 v[174:175], v[122:123], s[44:45] op_sel_hi:[1,0]
	v_exp_f32_e32 v172, v172
	v_exp_f32_e32 v174, v174
	v_exp_f32_e32 v173, v173
	v_exp_f32_e32 v175, v175
	v_pk_add_f32 v[168:169], v[168:169], 1.0 op_sel_hi:[1,0]
	v_pk_add_f32 v[170:171], v[170:171], 1.0 op_sel_hi:[1,0]
	v_rcp_f32_e32 v168, v168
	v_rcp_f32_e32 v170, v170
	v_rcp_f32_e32 v171, v171
	v_rcp_f32_e32 v169, v169
	v_pk_add_f32 v[172:173], v[172:173], 1.0 op_sel_hi:[1,0]
	v_pk_add_f32 v[174:175], v[174:175], 1.0 op_sel_hi:[1,0]
	v_rcp_f32_e32 v172, v172
	v_rcp_f32_e32 v174, v174
	v_rcp_f32_e32 v173, v173
	v_rcp_f32_e32 v175, v175
	v_pk_mul_f32 v[128:129], v[128:129], v[168:169]
	v_pk_mul_f32 v[126:127], v[126:127], v[170:171]
	v_pk_mul_f32 v[168:169], v[124:125], v[172:173]
	v_pk_mul_f32 v[124:125], v[122:123], v[174:175]
	v_cvt_pk_bf16_f32 v122, v126, v127
	v_cvt_pk_bf16_f32 v123, v128, v129
	s_lshl_b32 s18, s58, 3
	v_pk_mul_f32 v[126:127], v[120:121], s[44:45] op_sel_hi:[1,0]
	v_pk_mul_f32 v[128:129], v[118:119], s[44:45] op_sel_hi:[1,0]
	s_add_i32 s18, s18, s65
	v_exp_f32_e32 v128, v128
	v_exp_f32_e32 v126, v126
	v_exp_f32_e32 v127, v127
	v_exp_f32_e32 v129, v129
	s_ashr_i32 s19, s18, 31
	s_lshl_b64 s[58:59], s[18:19], 17
	v_cvt_pk_bf16_f32 v124, v124, v125
	v_cvt_pk_bf16_f32 v125, v168, v169
	v_lshl_add_u64 v[168:169], v[134:135], 0, s[58:59]
	global_store_dwordx4 v[168:169], v[122:125], off
	s_lshl_b64 s[60:61], s[18:19], 16
	s_andn2_b64 vcc, exec, s[48:49]
	v_pk_add_f32 v[122:123], v[126:127], 1.0 op_sel_hi:[1,0]
	v_pk_add_f32 v[124:125], v[128:129], 1.0 op_sel_hi:[1,0]
	v_pk_mul_f32 v[126:127], v[116:117], s[44:45] op_sel_hi:[1,0]
	v_pk_mul_f32 v[128:129], v[114:115], s[44:45] op_sel_hi:[1,0]
	v_exp_f32_e32 v126, v126
	v_exp_f32_e32 v128, v128
	v_exp_f32_e32 v127, v127
	v_exp_f32_e32 v129, v129
	v_rcp_f32_e32 v122, v122
	v_rcp_f32_e32 v123, v123
	v_pk_add_f32 v[126:127], v[126:127], 1.0 op_sel_hi:[1,0]
	v_pk_add_f32 v[128:129], v[128:129], 1.0 op_sel_hi:[1,0]
	v_rcp_f32_e32 v126, v126
	v_rcp_f32_e32 v128, v128
	v_rcp_f32_e32 v127, v127
	v_rcp_f32_e32 v129, v129
	v_rcp_f32_e32 v124, v124
	v_rcp_f32_e32 v125, v125
	v_pk_mul_f32 v[120:121], v[120:121], v[122:123]
	v_pk_mul_f32 v[122:123], v[116:117], v[126:127]
	v_pk_mul_f32 v[116:117], v[114:115], v[128:129]
	v_cvt_pk_bf16_f32 v115, v120, v121
	v_pk_mul_f32 v[120:121], v[112:113], s[44:45] op_sel_hi:[1,0]
	v_pk_mul_f32 v[118:119], v[118:119], v[124:125]
	v_exp_f32_e32 v120, v120
	v_exp_f32_e32 v121, v121
	v_cvt_pk_bf16_f32 v114, v118, v119
	v_mov_b32_e32 v119, s61
	v_or_b32_e32 v118, s60, v150
	v_cvt_pk_bf16_f32 v116, v116, v117
	v_cvt_pk_bf16_f32 v117, v122, v123
	v_pk_mul_f32 v[122:123], v[110:111], s[44:45] op_sel_hi:[1,0]
	v_lshl_add_u64 v[118:119], v[118:119], 1, s[10:11]
	v_exp_f32_e32 v122, v122
	v_exp_f32_e32 v123, v123
	global_store_dwordx4 v[118:119], v[114:117], off
	v_pk_mul_f32 v[118:119], v[108:109], s[44:45] op_sel_hi:[1,0]
	s_mov_b64 s[18:19], -1
	v_pk_add_f32 v[114:115], v[120:121], 1.0 op_sel_hi:[1,0]
	v_pk_mul_f32 v[120:121], v[106:107], s[44:45] op_sel_hi:[1,0]
	v_exp_f32_e32 v118, v118
	v_exp_f32_e32 v120, v120
	v_exp_f32_e32 v119, v119
	v_exp_f32_e32 v121, v121
	v_pk_add_f32 v[116:117], v[122:123], 1.0 op_sel_hi:[1,0]
	v_rcp_f32_e32 v114, v114
	v_rcp_f32_e32 v116, v116
	v_rcp_f32_e32 v117, v117
	v_rcp_f32_e32 v115, v115
	v_pk_add_f32 v[118:119], v[118:119], 1.0 op_sel_hi:[1,0]
	v_pk_add_f32 v[120:121], v[120:121], 1.0 op_sel_hi:[1,0]
	v_rcp_f32_e32 v118, v118
	v_rcp_f32_e32 v120, v120
	v_rcp_f32_e32 v119, v119
	v_rcp_f32_e32 v121, v121
	v_pk_mul_f32 v[112:113], v[112:113], v[114:115]
	v_pk_mul_f32 v[110:111], v[110:111], v[116:117]
	v_pk_mul_f32 v[114:115], v[108:109], v[118:119]
	v_pk_mul_f32 v[108:109], v[106:107], v[120:121]
	v_cvt_pk_bf16_f32 v106, v110, v111
	v_cvt_pk_bf16_f32 v107, v112, v113
	v_pk_mul_f32 v[110:111], v[104:105], s[44:45] op_sel_hi:[1,0]
	v_pk_mul_f32 v[112:113], v[102:103], s[44:45] op_sel_hi:[1,0]
	v_exp_f32_e32 v110, v110
	v_exp_f32_e32 v112, v112
	v_exp_f32_e32 v111, v111
	v_exp_f32_e32 v113, v113
	v_cvt_pk_bf16_f32 v108, v108, v109
	v_cvt_pk_bf16_f32 v109, v114, v115
	v_lshl_add_u64 v[114:115], v[136:137], 0, s[58:59]
	global_store_dwordx4 v[114:115], v[106:109], off
	s_cmp_lg_u64 s[38:39], 0
	s_cbranch_scc0 .Lalg_684
	s_barrier
; __device__ __forceinline__ f32x4 silu4(f32x4 x) { return x * sigmoid4(x); }
;     __device__ __forceinline__ void epi(Acc& acc, const Unit& u, int wr, int wc, int fr, int fq, LAS unsigned char*) const {
;     ...
;                 for (int bj = 0; bj < 2; ++bj) { const int n0 = u.pn * 256 + bj * 128 + wc * 32 + 8 * fq;
;                     f32x4 v0 = acc[ai][bj][m][0], v1 = acc[ai][bj][m][1];
;                     if (u.pm >= 128) { float* rp = ucs + ((((size_t)(n0 >> 4) * 4 + u.ks) * RC + (tok - RL)) * 16) + (n0 & 15); *(f32x4*)rp = v0; *(f32x4*)(rp + 4) = v1; continue; }
;                     if (zhalf) { v0 = silu4(v0); v1 = silu4(v1); }
;                     u32x4 w; w.x = pk2(v0[0], v0[1]); w.y = pk2(v0[2], v0[3]); w.z = pk2(v1[0], v1[1]); w.w = pk2(v1[2], v1[3]);
;                     if (zhalf) *(u32x4*)(SZ + ((((size_t)(u.pm * 8 + u.pn) * 256 + (tok & 255)) * 256) + (n0 & 255)) * 2) = w;
.Lalg_684:
	s_nop 1
	v_pk_add_f32 v[106:107], v[110:111], 1.0 op_sel_hi:[1,0]
	v_pk_add_f32 v[108:109], v[112:113], 1.0 op_sel_hi:[1,0]
	v_pk_mul_f32 v[110:111], v[100:101], s[44:45] op_sel_hi:[1,0]
	v_pk_mul_f32 v[112:113], v[98:99], s[44:45] op_sel_hi:[1,0]
	v_exp_f32_e32 v110, v110
	v_exp_f32_e32 v112, v112
	v_exp_f32_e32 v111, v111
	v_exp_f32_e32 v113, v113
	v_rcp_f32_e32 v106, v106
	v_rcp_f32_e32 v107, v107
	v_pk_add_f32 v[110:111], v[110:111], 1.0 op_sel_hi:[1,0]
	v_pk_add_f32 v[112:113], v[112:113], 1.0 op_sel_hi:[1,0]
	v_rcp_f32_e32 v110, v110
	v_rcp_f32_e32 v112, v112
	v_rcp_f32_e32 v111, v111
	v_rcp_f32_e32 v113, v113
	v_rcp_f32_e32 v108, v108
	v_rcp_f32_e32 v109, v109
	v_pk_mul_f32 v[104:105], v[104:105], v[106:107]
	v_pk_mul_f32 v[106:107], v[100:101], v[110:111]
	v_pk_mul_f32 v[100:101], v[98:99], v[112:113]
	v_cvt_pk_bf16_f32 v99, v104, v105
	v_pk_mul_f32 v[104:105], v[96:97], s[44:45] op_sel_hi:[1,0]
	v_pk_mul_f32 v[102:103], v[102:103], v[108:109]
	v_exp_f32_e32 v104, v104
	v_exp_f32_e32 v105, v105
	v_cvt_pk_bf16_f32 v98, v102, v103
	v_mov_b32_e32 v103, s61
	v_or_b32_e32 v102, s60, v152
	v_cvt_pk_bf16_f32 v100, v100, v101
	v_cvt_pk_bf16_f32 v101, v106, v107
	v_pk_mul_f32 v[106:107], v[94:95], s[44:45] op_sel_hi:[1,0]
	v_lshl_add_u64 v[102:103], v[102:103], 1, s[10:11]
	v_exp_f32_e32 v106, v106
	v_exp_f32_e32 v107, v107
	global_store_dwordx4 v[102:103], v[98:101], off
	v_pk_mul_f32 v[102:103], v[92:93], s[44:45] op_sel_hi:[1,0]
	s_nop 0
	v_pk_add_f32 v[98:99], v[104:105], 1.0 op_sel_hi:[1,0]
	v_pk_mul_f32 v[104:105], v[90:91], s[44:45] op_sel_hi:[1,0]
	v_exp_f32_e32 v102, v102
	v_exp_f32_e32 v104, v104
	v_exp_f32_e32 v103, v103
	v_exp_f32_e32 v105, v105
	v_pk_add_f32 v[100:101], v[106:107], 1.0 op_sel_hi:[1,0]
	v_rcp_f32_e32 v98, v98
	v_rcp_f32_e32 v100, v100
	v_rcp_f32_e32 v101, v101
	v_rcp_f32_e32 v99, v99
	v_pk_add_f32 v[102:103], v[102:103], 1.0 op_sel_hi:[1,0]
	v_pk_add_f32 v[104:105], v[104:105], 1.0 op_sel_hi:[1,0]
	v_rcp_f32_e32 v102, v102
	v_rcp_f32_e32 v104, v104
	v_rcp_f32_e32 v103, v103
	v_rcp_f32_e32 v105, v105
	v_pk_mul_f32 v[96:97], v[96:97], v[98:99]
	v_pk_mul_f32 v[94:95], v[94:95], v[100:101]
	v_pk_mul_f32 v[98:99], v[92:93], v[102:103]
	v_pk_mul_f32 v[92:93], v[90:91], v[104:105]
	v_cvt_pk_bf16_f32 v90, v94, v95
	v_cvt_pk_bf16_f32 v91, v96, v97
	v_pk_mul_f32 v[94:95], v[88:89], s[44:45] op_sel_hi:[1,0]
	v_pk_mul_f32 v[96:97], v[86:87], s[44:45] op_sel_hi:[1,0]
	v_exp_f32_e32 v94, v94
	v_exp_f32_e32 v96, v96
	v_exp_f32_e32 v95, v95
	v_exp_f32_e32 v97, v97
	v_cvt_pk_bf16_f32 v92, v92, v93
	v_cvt_pk_bf16_f32 v93, v98, v99
	v_lshl_add_u64 v[98:99], v[138:139], 0, s[58:59]
	global_store_dwordx4 v[98:99], v[90:93], off
	s_nop 1
	v_pk_add_f32 v[90:91], v[94:95], 1.0 op_sel_hi:[1,0]
	v_pk_add_f32 v[92:93], v[96:97], 1.0 op_sel_hi:[1,0]
	v_pk_mul_f32 v[94:95], v[84:85], s[44:45] op_sel_hi:[1,0]
	v_pk_mul_f32 v[96:97], v[82:83], s[44:45] op_sel_hi:[1,0]
	v_exp_f32_e32 v94, v94
	v_exp_f32_e32 v96, v96
	v_exp_f32_e32 v95, v95
	v_exp_f32_e32 v97, v97
	v_rcp_f32_e32 v90, v90
	v_rcp_f32_e32 v91, v91
	v_pk_add_f32 v[94:95], v[94:95], 1.0 op_sel_hi:[1,0]
	v_pk_add_f32 v[96:97], v[96:97], 1.0 op_sel_hi:[1,0]
	v_rcp_f32_e32 v94, v94
	v_rcp_f32_e32 v96, v96
	v_rcp_f32_e32 v95, v95
	v_rcp_f32_e32 v97, v97
	v_rcp_f32_e32 v92, v92
	v_rcp_f32_e32 v93, v93
	v_pk_mul_f32 v[88:89], v[88:89], v[90:91]
	v_pk_mul_f32 v[90:91], v[84:85], v[94:95]
	v_pk_mul_f32 v[84:85], v[82:83], v[96:97]
	v_cvt_pk_bf16_f32 v83, v88, v89
	v_pk_mul_f32 v[88:89], v[80:81], s[44:45] op_sel_hi:[1,0]
	v_pk_mul_f32 v[86:87], v[86:87], v[92:93]
	v_exp_f32_e32 v88, v88
	v_exp_f32_e32 v89, v89
	v_cvt_pk_bf16_f32 v82, v86, v87
	v_mov_b32_e32 v87, s61
	v_or_b32_e32 v86, s60, v154
	v_cvt_pk_bf16_f32 v84, v84, v85
	v_cvt_pk_bf16_f32 v85, v90, v91
	v_pk_mul_f32 v[90:91], v[78:79], s[44:45] op_sel_hi:[1,0]
	v_lshl_add_u64 v[86:87], v[86:87], 1, s[10:11]
	v_exp_f32_e32 v90, v90
	v_exp_f32_e32 v91, v91
	global_store_dwordx4 v[86:87], v[82:85], off
	v_pk_mul_f32 v[86:87], v[76:77], s[44:45] op_sel_hi:[1,0]
	s_nop 0
	v_pk_add_f32 v[82:83], v[88:89], 1.0 op_sel_hi:[1,0]
	v_pk_mul_f32 v[88:89], v[74:75], s[44:45] op_sel_hi:[1,0]
	v_exp_f32_e32 v86, v86
	v_exp_f32_e32 v88, v88
	v_exp_f32_e32 v87, v87
	v_exp_f32_e32 v89, v89
	v_pk_add_f32 v[84:85], v[90:91], 1.0 op_sel_hi:[1,0]
	v_rcp_f32_e32 v82, v82
	v_rcp_f32_e32 v84, v84
	v_rcp_f32_e32 v85, v85
	v_rcp_f32_e32 v83, v83
	v_pk_add_f32 v[86:87], v[86:87], 1.0 op_sel_hi:[1,0]
	v_pk_add_f32 v[88:89], v[88:89], 1.0 op_sel_hi:[1,0]
	v_rcp_f32_e32 v86, v86
	v_rcp_f32_e32 v88, v88
	v_rcp_f32_e32 v87, v87
	v_rcp_f32_e32 v89, v89
	v_pk_mul_f32 v[80:81], v[80:81], v[82:83]
	v_pk_mul_f32 v[78:79], v[78:79], v[84:85]
	v_pk_mul_f32 v[82:83], v[76:77], v[86:87]
	v_pk_mul_f32 v[76:77], v[74:75], v[88:89]
	v_cvt_pk_bf16_f32 v74, v78, v79
	v_cvt_pk_bf16_f32 v75, v80, v81
	v_pk_mul_f32 v[78:79], v[72:73], s[44:45] op_sel_hi:[1,0]
	v_pk_mul_f32 v[80:81], v[70:71], s[44:45] op_sel_hi:[1,0]
	v_exp_f32_e32 v78, v78
	v_exp_f32_e32 v80, v80
	v_exp_f32_e32 v79, v79
	v_exp_f32_e32 v81, v81
	v_cvt_pk_bf16_f32 v76, v76, v77
	v_cvt_pk_bf16_f32 v77, v82, v83
	v_lshl_add_u64 v[82:83], v[140:141], 0, s[58:59]
	global_store_dwordx4 v[82:83], v[74:77], off
	s_nop 1
	v_pk_add_f32 v[74:75], v[78:79], 1.0 op_sel_hi:[1,0]
	v_pk_add_f32 v[76:77], v[80:81], 1.0 op_sel_hi:[1,0]
	v_pk_mul_f32 v[78:79], v[68:69], s[44:45] op_sel_hi:[1,0]
	v_pk_mul_f32 v[80:81], v[66:67], s[44:45] op_sel_hi:[1,0]
	v_exp_f32_e32 v78, v78
	v_exp_f32_e32 v80, v80
	v_exp_f32_e32 v79, v79
	v_exp_f32_e32 v81, v81
	v_rcp_f32_e32 v74, v74
	v_rcp_f32_e32 v75, v75
; __device__ __forceinline__ f32x4 silu4(f32x4 x) { return x * sigmoid4(x); }
;     __device__ __forceinline__ void epi(Acc& acc, const Unit& u, int wr, int wc, int fr, int fq, LAS unsigned char*) const {
;     ...
;                 for (int bj = 0; bj < 2; ++bj) { const int n0 = u.pn * 256 + bj * 128 + wc * 32 + 8 * fq;
;                     f32x4 v0 = acc[ai][bj][m][0], v1 = acc[ai][bj][m][1];
;                     if (u.pm >= 128) { float* rp = ucs + ((((size_t)(n0 >> 4) * 4 + u.ks) * RC + (tok - RL)) * 16) + (n0 & 15); *(f32x4*)rp = v0; *(f32x4*)(rp + 4) = v1; continue; }
;                     if (zhalf) { v0 = silu4(v0); v1 = silu4(v1); }
;                     u32x4 w; w.x = pk2(v0[0], v0[1]); w.y = pk2(v0[2], v0[3]); w.z = pk2(v1[0], v1[1]); w.w = pk2(v1[2], v1[3]);
;                     if (zhalf) *(u32x4*)(SZ + ((((size_t)(u.pm * 8 + u.pn) * 256 + (tok & 255)) * 256) + (n0 & 255)) * 2) = w;
	v_pk_add_f32 v[78:79], v[78:79], 1.0 op_sel_hi:[1,0]
	v_pk_add_f32 v[80:81], v[80:81], 1.0 op_sel_hi:[1,0]
	v_rcp_f32_e32 v78, v78
	v_rcp_f32_e32 v80, v80
	v_rcp_f32_e32 v79, v79
	v_rcp_f32_e32 v81, v81
	v_rcp_f32_e32 v76, v76
	v_rcp_f32_e32 v77, v77
	v_pk_mul_f32 v[72:73], v[72:73], v[74:75]
	v_pk_mul_f32 v[74:75], v[68:69], v[78:79]
	v_pk_mul_f32 v[68:69], v[66:67], v[80:81]
	v_cvt_pk_bf16_f32 v67, v72, v73
	v_pk_mul_f32 v[72:73], v[64:65], s[44:45] op_sel_hi:[1,0]
	v_pk_mul_f32 v[70:71], v[70:71], v[76:77]
	v_exp_f32_e32 v72, v72
	v_exp_f32_e32 v73, v73
	v_cvt_pk_bf16_f32 v66, v70, v71
	v_mov_b32_e32 v71, s61
	v_or_b32_e32 v70, s60, v156
	v_cvt_pk_bf16_f32 v68, v68, v69
	v_cvt_pk_bf16_f32 v69, v74, v75
	v_pk_mul_f32 v[74:75], v[62:63], s[44:45] op_sel_hi:[1,0]
	v_lshl_add_u64 v[70:71], v[70:71], 1, s[10:11]
	v_exp_f32_e32 v74, v74
	v_exp_f32_e32 v75, v75
	global_store_dwordx4 v[70:71], v[66:69], off
	v_pk_mul_f32 v[70:71], v[60:61], s[44:45] op_sel_hi:[1,0]
	s_nop 0
	v_pk_add_f32 v[66:67], v[72:73], 1.0 op_sel_hi:[1,0]
	v_pk_mul_f32 v[72:73], v[58:59], s[44:45] op_sel_hi:[1,0]
	v_exp_f32_e32 v70, v70
	v_exp_f32_e32 v72, v72
	v_exp_f32_e32 v71, v71
	v_exp_f32_e32 v73, v73
	v_pk_add_f32 v[68:69], v[74:75], 1.0 op_sel_hi:[1,0]
	v_rcp_f32_e32 v66, v66
	v_rcp_f32_e32 v68, v68
	v_rcp_f32_e32 v69, v69
	v_rcp_f32_e32 v67, v67
	v_pk_add_f32 v[70:71], v[70:71], 1.0 op_sel_hi:[1,0]
	v_pk_add_f32 v[72:73], v[72:73], 1.0 op_sel_hi:[1,0]
	v_rcp_f32_e32 v70, v70
	v_rcp_f32_e32 v72, v72
	v_rcp_f32_e32 v71, v71
	v_rcp_f32_e32 v73, v73
	v_pk_mul_f32 v[64:65], v[64:65], v[66:67]
	v_pk_mul_f32 v[62:63], v[62:63], v[68:69]
	v_pk_mul_f32 v[66:67], v[60:61], v[70:71]
	v_pk_mul_f32 v[60:61], v[58:59], v[72:73]
	v_cvt_pk_bf16_f32 v58, v62, v63
	v_cvt_pk_bf16_f32 v59, v64, v65
	v_pk_mul_f32 v[62:63], v[56:57], s[44:45] op_sel_hi:[1,0]
	v_pk_mul_f32 v[64:65], v[54:55], s[44:45] op_sel_hi:[1,0]
	v_exp_f32_e32 v62, v62
	v_exp_f32_e32 v64, v64
	v_exp_f32_e32 v63, v63
	v_exp_f32_e32 v65, v65
	v_cvt_pk_bf16_f32 v60, v60, v61
	v_cvt_pk_bf16_f32 v61, v66, v67
	v_lshl_add_u64 v[66:67], v[142:143], 0, s[58:59]
	global_store_dwordx4 v[66:67], v[58:61], off
	s_nop 1
	v_pk_add_f32 v[58:59], v[62:63], 1.0 op_sel_hi:[1,0]
	v_pk_add_f32 v[60:61], v[64:65], 1.0 op_sel_hi:[1,0]
	v_pk_mul_f32 v[62:63], v[52:53], s[44:45] op_sel_hi:[1,0]
	v_pk_mul_f32 v[64:65], v[50:51], s[44:45] op_sel_hi:[1,0]
	v_exp_f32_e32 v62, v62
	v_exp_f32_e32 v64, v64
	v_exp_f32_e32 v63, v63
	v_exp_f32_e32 v65, v65
	v_rcp_f32_e32 v58, v58
	v_rcp_f32_e32 v59, v59
	v_pk_add_f32 v[62:63], v[62:63], 1.0 op_sel_hi:[1,0]
	v_pk_add_f32 v[64:65], v[64:65], 1.0 op_sel_hi:[1,0]
	v_rcp_f32_e32 v62, v62
	v_rcp_f32_e32 v64, v64
	v_rcp_f32_e32 v63, v63
	v_rcp_f32_e32 v65, v65
	v_rcp_f32_e32 v60, v60
	v_rcp_f32_e32 v61, v61
	v_pk_mul_f32 v[56:57], v[56:57], v[58:59]
	v_pk_mul_f32 v[58:59], v[52:53], v[62:63]
	v_pk_mul_f32 v[52:53], v[50:51], v[64:65]
	v_cvt_pk_bf16_f32 v51, v56, v57
	v_pk_mul_f32 v[56:57], v[48:49], s[44:45] op_sel_hi:[1,0]
	v_pk_mul_f32 v[54:55], v[54:55], v[60:61]
	v_exp_f32_e32 v56, v56
	v_exp_f32_e32 v57, v57
	v_cvt_pk_bf16_f32 v50, v54, v55
	v_mov_b32_e32 v55, s61
	v_or_b32_e32 v54, s60, v158
	v_cvt_pk_bf16_f32 v52, v52, v53
	v_cvt_pk_bf16_f32 v53, v58, v59
	v_pk_mul_f32 v[58:59], v[46:47], s[44:45] op_sel_hi:[1,0]
	v_lshl_add_u64 v[54:55], v[54:55], 1, s[10:11]
	v_exp_f32_e32 v58, v58
	v_exp_f32_e32 v59, v59
	global_store_dwordx4 v[54:55], v[50:53], off
	v_pk_mul_f32 v[54:55], v[44:45], s[44:45] op_sel_hi:[1,0]
	s_nop 0
	v_pk_add_f32 v[50:51], v[56:57], 1.0 op_sel_hi:[1,0]
	v_pk_mul_f32 v[56:57], v[42:43], s[44:45] op_sel_hi:[1,0]
	v_exp_f32_e32 v54, v54
	v_exp_f32_e32 v56, v56
	v_exp_f32_e32 v55, v55
	v_exp_f32_e32 v57, v57
	v_pk_add_f32 v[52:53], v[58:59], 1.0 op_sel_hi:[1,0]
	v_rcp_f32_e32 v50, v50
	v_rcp_f32_e32 v52, v52
	v_rcp_f32_e32 v53, v53
	v_rcp_f32_e32 v51, v51
	v_pk_add_f32 v[54:55], v[54:55], 1.0 op_sel_hi:[1,0]
	v_pk_add_f32 v[56:57], v[56:57], 1.0 op_sel_hi:[1,0]
	v_rcp_f32_e32 v54, v54
	v_rcp_f32_e32 v56, v56
	v_rcp_f32_e32 v55, v55
	v_rcp_f32_e32 v57, v57
	v_pk_mul_f32 v[48:49], v[48:49], v[50:51]
	v_pk_mul_f32 v[46:47], v[46:47], v[52:53]
	v_pk_mul_f32 v[50:51], v[44:45], v[54:55]
	v_pk_mul_f32 v[44:45], v[42:43], v[56:57]
	v_cvt_pk_bf16_f32 v42, v46, v47
	v_cvt_pk_bf16_f32 v43, v48, v49
	v_pk_mul_f32 v[46:47], v[40:41], s[44:45] op_sel_hi:[1,0]
	v_pk_mul_f32 v[48:49], v[38:39], s[44:45] op_sel_hi:[1,0]
	v_exp_f32_e32 v46, v46
	v_exp_f32_e32 v48, v48
	v_exp_f32_e32 v47, v47
	v_exp_f32_e32 v49, v49
	v_cvt_pk_bf16_f32 v44, v44, v45
	v_cvt_pk_bf16_f32 v45, v50, v51
	v_lshl_add_u64 v[50:51], v[144:145], 0, s[58:59]
	global_store_dwordx4 v[50:51], v[42:45], off
	s_nop 1
	v_pk_add_f32 v[42:43], v[46:47], 1.0 op_sel_hi:[1,0]
	v_pk_add_f32 v[44:45], v[48:49], 1.0 op_sel_hi:[1,0]
	v_pk_mul_f32 v[46:47], v[36:37], s[44:45] op_sel_hi:[1,0]
	v_pk_mul_f32 v[48:49], v[34:35], s[44:45] op_sel_hi:[1,0]
	v_exp_f32_e32 v46, v46
	v_exp_f32_e32 v48, v48
	v_exp_f32_e32 v47, v47
	v_exp_f32_e32 v49, v49
	v_rcp_f32_e32 v42, v42
	v_rcp_f32_e32 v43, v43
	v_pk_add_f32 v[46:47], v[46:47], 1.0 op_sel_hi:[1,0]
	v_pk_add_f32 v[48:49], v[48:49], 1.0 op_sel_hi:[1,0]
	v_rcp_f32_e32 v46, v46
	v_rcp_f32_e32 v48, v48
	v_rcp_f32_e32 v47, v47
	v_rcp_f32_e32 v49, v49
	v_rcp_f32_e32 v44, v44
	v_rcp_f32_e32 v45, v45
	v_pk_mul_f32 v[40:41], v[40:41], v[42:43]
	v_pk_mul_f32 v[42:43], v[36:37], v[46:47]
	v_pk_mul_f32 v[36:37], v[34:35], v[48:49]
; __device__ __forceinline__ f32x4 silu4(f32x4 x) { return x * sigmoid4(x); }
;     __device__ __forceinline__ void epi(Acc& acc, const Unit& u, int wr, int wc, int fr, int fq, LAS unsigned char*) const {
;     ...
;                 for (int bj = 0; bj < 2; ++bj) { const int n0 = u.pn * 256 + bj * 128 + wc * 32 + 8 * fq;
;                     f32x4 v0 = acc[ai][bj][m][0], v1 = acc[ai][bj][m][1];
;                     if (u.pm >= 128) { float* rp = ucs + ((((size_t)(n0 >> 4) * 4 + u.ks) * RC + (tok - RL)) * 16) + (n0 & 15); *(f32x4*)rp = v0; *(f32x4*)(rp + 4) = v1; continue; }
;                     if (zhalf) { v0 = silu4(v0); v1 = silu4(v1); }
;                     u32x4 w; w.x = pk2(v0[0], v0[1]); w.y = pk2(v0[2], v0[3]); w.z = pk2(v1[0], v1[1]); w.w = pk2(v1[2], v1[3]);
;                     if (zhalf) *(u32x4*)(SZ + ((((size_t)(u.pm * 8 + u.pn) * 256 + (tok & 255)) * 256) + (n0 & 255)) * 2) = w;
	v_cvt_pk_bf16_f32 v35, v40, v41
	v_pk_mul_f32 v[40:41], v[32:33], s[44:45] op_sel_hi:[1,0]
	v_pk_mul_f32 v[38:39], v[38:39], v[44:45]
	v_exp_f32_e32 v40, v40
	v_exp_f32_e32 v41, v41
	v_cvt_pk_bf16_f32 v34, v38, v39
	v_mov_b32_e32 v39, s61
	v_or_b32_e32 v38, s60, v160
	v_cvt_pk_bf16_f32 v36, v36, v37
	v_cvt_pk_bf16_f32 v37, v42, v43
	v_pk_mul_f32 v[42:43], v[30:31], s[44:45] op_sel_hi:[1,0]
	v_lshl_add_u64 v[38:39], v[38:39], 1, s[10:11]
	v_exp_f32_e32 v42, v42
	v_exp_f32_e32 v43, v43
	global_store_dwordx4 v[38:39], v[34:37], off
	v_pk_mul_f32 v[38:39], v[28:29], s[44:45] op_sel_hi:[1,0]
	s_nop 0
	v_pk_add_f32 v[34:35], v[40:41], 1.0 op_sel_hi:[1,0]
	v_pk_mul_f32 v[40:41], v[26:27], s[44:45] op_sel_hi:[1,0]
	v_exp_f32_e32 v38, v38
	v_exp_f32_e32 v40, v40
	v_exp_f32_e32 v39, v39
	v_exp_f32_e32 v41, v41
	v_pk_add_f32 v[36:37], v[42:43], 1.0 op_sel_hi:[1,0]
	v_rcp_f32_e32 v34, v34
	v_rcp_f32_e32 v36, v36
	v_rcp_f32_e32 v37, v37
	v_rcp_f32_e32 v35, v35
	v_pk_add_f32 v[38:39], v[38:39], 1.0 op_sel_hi:[1,0]
	v_pk_add_f32 v[40:41], v[40:41], 1.0 op_sel_hi:[1,0]
	v_rcp_f32_e32 v38, v38
	v_rcp_f32_e32 v40, v40
	v_rcp_f32_e32 v39, v39
	v_rcp_f32_e32 v41, v41
	v_pk_mul_f32 v[32:33], v[32:33], v[34:35]
	v_pk_mul_f32 v[30:31], v[30:31], v[36:37]
	v_pk_mul_f32 v[34:35], v[28:29], v[38:39]
	v_pk_mul_f32 v[28:29], v[26:27], v[40:41]
	v_cvt_pk_bf16_f32 v26, v30, v31
	v_cvt_pk_bf16_f32 v27, v32, v33
	v_pk_mul_f32 v[30:31], v[24:25], s[44:45] op_sel_hi:[1,0]
	v_pk_mul_f32 v[32:33], v[22:23], s[44:45] op_sel_hi:[1,0]
	v_exp_f32_e32 v30, v30
	v_exp_f32_e32 v32, v32
	v_exp_f32_e32 v31, v31
	v_exp_f32_e32 v33, v33
	v_cvt_pk_bf16_f32 v28, v28, v29
	v_cvt_pk_bf16_f32 v29, v34, v35
	v_lshl_add_u64 v[34:35], v[146:147], 0, s[58:59]
	global_store_dwordx4 v[34:35], v[26:29], off
	s_nop 1
	v_pk_add_f32 v[26:27], v[30:31], 1.0 op_sel_hi:[1,0]
	v_pk_add_f32 v[28:29], v[32:33], 1.0 op_sel_hi:[1,0]
	v_pk_mul_f32 v[30:31], v[20:21], s[44:45] op_sel_hi:[1,0]
	v_pk_mul_f32 v[32:33], v[18:19], s[44:45] op_sel_hi:[1,0]
	v_exp_f32_e32 v30, v30
	v_exp_f32_e32 v32, v32
	v_exp_f32_e32 v31, v31
	v_exp_f32_e32 v33, v33
	v_rcp_f32_e32 v26, v26
	v_rcp_f32_e32 v27, v27
	v_pk_add_f32 v[30:31], v[30:31], 1.0 op_sel_hi:[1,0]
	v_pk_add_f32 v[32:33], v[32:33], 1.0 op_sel_hi:[1,0]
	v_rcp_f32_e32 v30, v30
	v_rcp_f32_e32 v32, v32
	v_rcp_f32_e32 v31, v31
	v_rcp_f32_e32 v33, v33
	v_rcp_f32_e32 v28, v28
	v_rcp_f32_e32 v29, v29
	v_pk_mul_f32 v[24:25], v[24:25], v[26:27]
	v_pk_mul_f32 v[26:27], v[20:21], v[30:31]
	v_pk_mul_f32 v[20:21], v[18:19], v[32:33]
	v_cvt_pk_bf16_f32 v19, v24, v25
	v_pk_mul_f32 v[24:25], v[16:17], s[44:45] op_sel_hi:[1,0]
	v_pk_mul_f32 v[22:23], v[22:23], v[28:29]
	v_exp_f32_e32 v24, v24
	v_exp_f32_e32 v25, v25
	v_cvt_pk_bf16_f32 v18, v22, v23
	v_mov_b32_e32 v23, s61
	v_or_b32_e32 v22, s60, v162
	v_cvt_pk_bf16_f32 v20, v20, v21
	v_cvt_pk_bf16_f32 v21, v26, v27
	v_pk_mul_f32 v[26:27], v[14:15], s[44:45] op_sel_hi:[1,0]
	v_lshl_add_u64 v[22:23], v[22:23], 1, s[10:11]
	v_exp_f32_e32 v26, v26
	v_exp_f32_e32 v27, v27
	global_store_dwordx4 v[22:23], v[18:21], off
	v_pk_mul_f32 v[22:23], v[12:13], s[44:45] op_sel_hi:[1,0]
	s_nop 0
	v_pk_add_f32 v[18:19], v[24:25], 1.0 op_sel_hi:[1,0]
	v_pk_mul_f32 v[24:25], v[10:11], s[44:45] op_sel_hi:[1,0]
	v_exp_f32_e32 v22, v22
	v_exp_f32_e32 v24, v24
	v_exp_f32_e32 v23, v23
	v_exp_f32_e32 v25, v25
	v_pk_add_f32 v[20:21], v[26:27], 1.0 op_sel_hi:[1,0]
	v_rcp_f32_e32 v18, v18
	v_rcp_f32_e32 v20, v20
	v_rcp_f32_e32 v21, v21
	v_rcp_f32_e32 v19, v19
	v_pk_add_f32 v[22:23], v[22:23], 1.0 op_sel_hi:[1,0]
	v_pk_add_f32 v[24:25], v[24:25], 1.0 op_sel_hi:[1,0]
	v_rcp_f32_e32 v22, v22
	v_rcp_f32_e32 v24, v24
	v_rcp_f32_e32 v23, v23
	v_rcp_f32_e32 v25, v25
	v_pk_mul_f32 v[16:17], v[16:17], v[18:19]
	v_pk_mul_f32 v[14:15], v[14:15], v[20:21]
	v_pk_mul_f32 v[18:19], v[12:13], v[22:23]
	v_pk_mul_f32 v[12:13], v[10:11], v[24:25]
	v_cvt_pk_bf16_f32 v10, v14, v15
	v_cvt_pk_bf16_f32 v11, v16, v17
	v_pk_mul_f32 v[14:15], v[8:9], s[44:45] op_sel_hi:[1,0]
	v_pk_mul_f32 v[16:17], v[6:7], s[44:45] op_sel_hi:[1,0]
	v_exp_f32_e32 v14, v14
	v_exp_f32_e32 v16, v16
	v_exp_f32_e32 v15, v15
	v_exp_f32_e32 v17, v17
	v_cvt_pk_bf16_f32 v12, v12, v13
	v_cvt_pk_bf16_f32 v13, v18, v19
	v_lshl_add_u64 v[18:19], v[148:149], 0, s[58:59]
	global_store_dwordx4 v[18:19], v[10:13], off
	s_nop 1
	v_pk_add_f32 v[10:11], v[14:15], 1.0 op_sel_hi:[1,0]
	v_pk_add_f32 v[12:13], v[16:17], 1.0 op_sel_hi:[1,0]
	v_pk_mul_f32 v[14:15], v[4:5], s[44:45] op_sel_hi:[1,0]
	v_pk_mul_f32 v[16:17], v[2:3], s[44:45] op_sel_hi:[1,0]
	v_exp_f32_e32 v14, v14
	v_exp_f32_e32 v16, v16
	v_exp_f32_e32 v15, v15
	v_exp_f32_e32 v17, v17
	v_rcp_f32_e32 v12, v12
	v_rcp_f32_e32 v13, v13
	v_pk_add_f32 v[14:15], v[14:15], 1.0 op_sel_hi:[1,0]
	v_pk_add_f32 v[16:17], v[16:17], 1.0 op_sel_hi:[1,0]
	v_rcp_f32_e32 v10, v10
	v_rcp_f32_e32 v11, v11
	v_rcp_f32_e32 v16, v16
	v_rcp_f32_e32 v14, v14
	v_rcp_f32_e32 v15, v15
	v_rcp_f32_e32 v17, v17
	v_pk_mul_f32 v[6:7], v[6:7], v[12:13]
	v_pk_mul_f32 v[8:9], v[8:9], v[10:11]
	v_pk_mul_f32 v[10:11], v[4:5], v[14:15]
	v_pk_mul_f32 v[4:5], v[2:3], v[16:17]
	v_cvt_pk_bf16_f32 v2, v6, v7
	v_mov_b32_e32 v7, s61
	v_or_b32_e32 v6, s60, v164
	v_cvt_pk_bf16_f32 v3, v8, v9
	v_cvt_pk_bf16_f32 v4, v4, v5
	v_cvt_pk_bf16_f32 v5, v10, v11
	v_lshl_add_u64 v[6:7], v[6:7], 1, s[10:11]
	global_store_dwordx4 v[6:7], v[2:5], off
	s_cbranch_vccnz .LBB0_671
	s_andn2_b64 vcc, exec, s[8:9]
	s_cbranch_vccnz .LBB0_670
	s_barrier
	s_branch .LBB0_670

; #define G8_STA(bufoff, ptr, sg, h) G8_STAGE1(bufoff, (ptr) + (h) * ((sg) ? hA1 : hA0), ((sg) ? voffA1 : voffA0), ((sg) ? r64A1 : r64A0))
; #define G8_STB(bufoff, ptr, sg, h) G8_STAGE1(bufoff, (ptr) + (h) * ((sg) ? hB1 : hB0), ((sg) ? voffB1 : voffB0), ((sg) ? r64B1 : r64B0))
; #define G8_LDA(dst, b, h) do { _Pragma("unroll") for (int m = 0; m < 4; ++m) _Pragma("unroll") for (int k = 0; k < 2; ++k) dst[m][k] = *(const LAS bf16x8*)(lds + G8_SA(b, h) + aoff + m * 2048 + k * 1024); } while (0)
; #define G8_LDB(dst, b, h) do { _Pragma("unroll") for (int n = 0; n < 2; ++n) _Pragma("unroll") for (int k = 0; k < 2; ++k) dst[n][k] = *(const LAS bf16x8*)(lds + G8_SB(b, h) + boff + n * 2048 + k * 1024); } while (0)
; #define G8_MMA(ai, bj, At, Bt) do { __builtin_amdgcn_s_setprio(1); _Pragma("unroll") for (int m = 0; m < 4; ++m) _Pragma("unroll") for (int n = 0; n < 2; ++n) _Pragma("unroll") for (int k = 0; k < 2; ++k) \
;         acc[ai][bj][m][n] = __builtin_amdgcn_mfma_f32_16x16x32_bf16(Bt[n][k], At[m][k], acc[ai][bj][m][n], 0, 0, 0); __builtin_amdgcn_s_setprio(0); } while (0)
; #define G8_WAIT_V(n) asm volatile("s_waitcnt vmcnt(" #n ")" ::: "memory")
; #define G8_WAIT_L(n) asm volatile("s_waitcnt lgkmcnt(" #n ")" ::: "memory")
; #define G8_BAR __builtin_amdgcn_s_barrier()
; #define G8_SCHED __builtin_amdgcn_sched_barrier(0)
; template <class P>
; __device__ __forceinline__ void gemm_phase(LAS unsigned char* lds, const P& p, const int G, const int c) {
;     ...
;             G8_LDB(B0, 1, 0); G8_LDB(B1, 1, 1); G8_SCHED; G8_LDA(At, 1, 0); G8_STA(G8_SA(0, 1), a2, sg2, 1);
;             G8_WAIT_V(8); G8_WAIT_L(0); G8_BAR; G8_MMA(0, 0, At, B0); G8_MMA(0, 1, At, B1); G8_BAR; G8_SCHED;
;             G8_LDA(At, 1, 1); G8_STB(G8_SB(1, 0), b3, sg2, 0); G8_STB(G8_SB(1, 1), b3, sg2, 1); G8_STA(G8_SA(1, 0), a3, sg2, 0);
;             G8_WAIT_V(8); G8_WAIT_L(0); G8_BAR; G8_MMA(1, 0, At, B0); G8_MMA(1, 1, At, B1); G8_BAR; G8_SCHED;
;         }
.Lmid_707:
	s_barrier
	s_add_i32 s65, 0, 0x18000
	v_add_u32_e32 v84, s65, v229
	s_add_i32 s66, 0, 0x1c000
	ds_read_b128 v[68:71], v84
	ds_read_b128 v[72:75], v84 offset:1024
	ds_read_b128 v[76:79], v84 offset:2048
	ds_read_b128 v[138:141], v84 offset:3072
	v_add_u32_e32 v84, s66, v229
	ds_read_b128 v[142:145], v84
	ds_read_b128 v[154:157], v84 offset:1024
	ds_read_b128 v[158:161], v84 offset:2048
	ds_read_b128 v[162:165], v84 offset:3072
	s_mov_b32 m0, s27
	v_lshl_add_u64 v[84:85], v[200:201], 0, s[14:15]
	ds_read_b128 v[166:169], v232 offset:32768
	ds_read_b128 v[170:173], v232 offset:33792
	ds_read_b128 v[174:177], v232 offset:34816
	ds_read_b128 v[178:181], v232 offset:35840
	ds_read_b128 v[182:185], v232 offset:36864
	ds_read_b128 v[186:189], v232 offset:37888
	ds_read_b128 v[190:193], v232 offset:38912
	ds_read_b128 v[194:197], v232 offset:39936
	global_load_lds_dwordx4 v[84:85], off
	v_lshl_add_u64 v[84:85], v[200:201], 0, s[16:17]
	s_mov_b32 m0, s31
	s_nop 0
	global_load_lds_dwordx4 v[84:85], off
	s_waitcnt vmcnt(8)
	s_waitcnt lgkmcnt(0)
	s_barrier
	s_waitcnt lgkmcnt(0)
	v_mfma_f32_16x16x32_bf16 v[150:153], v[68:71], v[166:169], v[150:153]
	v_mfma_f32_16x16x32_bf16 v[146:149], v[76:79], v[166:169], v[146:149]
	v_mfma_f32_16x16x32_bf16 v[126:129], v[68:71], v[174:177], v[126:129]
	v_mfma_f32_16x16x32_bf16 v[122:125], v[76:79], v[174:177], v[122:125]
	v_mfma_f32_16x16x32_bf16 v[110:113], v[68:71], v[182:185], v[110:113]
	v_mfma_f32_16x16x32_bf16 v[106:109], v[76:79], v[182:185], v[106:109]
	v_mfma_f32_16x16x32_bf16 v[94:97], v[68:71], v[190:193], v[94:97]
	v_mfma_f32_16x16x32_bf16 v[90:93], v[76:79], v[190:193], v[90:93]
	v_mfma_f32_16x16x32_bf16 v[150:153], v[72:75], v[170:173], v[150:153]
	v_mfma_f32_16x16x32_bf16 v[146:149], v[138:141], v[170:173], v[146:149]
	v_mfma_f32_16x16x32_bf16 v[126:129], v[72:75], v[178:181], v[126:129]
	v_mfma_f32_16x16x32_bf16 v[122:125], v[138:141], v[178:181], v[122:125]
	v_mfma_f32_16x16x32_bf16 v[110:113], v[72:75], v[186:189], v[110:113]
	v_mfma_f32_16x16x32_bf16 v[106:109], v[138:141], v[186:189], v[106:109]
	v_mfma_f32_16x16x32_bf16 v[94:97], v[72:75], v[194:197], v[94:97]
	v_mfma_f32_16x16x32_bf16 v[90:93], v[138:141], v[194:197], v[90:93]
	v_mfma_f32_16x16x32_bf16 v[134:137], v[142:145], v[166:169], v[134:137]
	v_mfma_f32_16x16x32_bf16 v[130:133], v[158:161], v[166:169], v[130:133]
	v_mfma_f32_16x16x32_bf16 v[118:121], v[142:145], v[174:177], v[118:121]
	v_mfma_f32_16x16x32_bf16 v[114:117], v[158:161], v[174:177], v[114:117]
	v_mfma_f32_16x16x32_bf16 v[102:105], v[142:145], v[182:185], v[102:105]
	v_mfma_f32_16x16x32_bf16 v[98:101], v[158:161], v[182:185], v[98:101]
	v_mfma_f32_16x16x32_bf16 v[84:87], v[142:145], v[190:193], v[86:89]
	v_mfma_f32_16x16x32_bf16 v[80:83], v[158:161], v[190:193], v[80:83]
	v_mfma_f32_16x16x32_bf16 v[134:137], v[154:157], v[170:173], v[134:137]
	v_mfma_f32_16x16x32_bf16 v[130:133], v[162:165], v[170:173], v[130:133]
	v_mfma_f32_16x16x32_bf16 v[118:121], v[154:157], v[178:181], v[118:121]
	v_mfma_f32_16x16x32_bf16 v[114:117], v[162:165], v[178:181], v[114:117]
	v_mfma_f32_16x16x32_bf16 v[102:105], v[154:157], v[186:189], v[102:105]
	v_mfma_f32_16x16x32_bf16 v[98:101], v[162:165], v[186:189], v[98:101]
	v_mfma_f32_16x16x32_bf16 v[86:89], v[154:157], v[194:197], v[84:87]
	v_mfma_f32_16x16x32_bf16 v[82:85], v[162:165], v[194:197], v[80:83]
	s_barrier
	s_add_i32 s65, s65, s24
	v_lshl_add_u64 v[80:81], v[198:199], 0, s[36:37]
	s_mov_b32 m0, s65
	ds_read_b128 v[166:169], v232 offset:49152
	ds_read_b128 v[170:173], v232 offset:50176
	ds_read_b128 v[174:177], v232 offset:51200
	ds_read_b128 v[178:181], v232 offset:52224
	ds_read_b128 v[182:185], v232 offset:53248
	ds_read_b128 v[186:189], v232 offset:54272
	ds_read_b128 v[190:193], v232 offset:55296
	ds_read_b128 v[194:197], v232 offset:56320
	global_load_lds_dwordx4 v[80:81], off
	v_lshl_add_u64 v[80:81], v[198:199], 0, s[38:39]
	s_add_i32 m0, s65, 0x2000
	s_add_i32 s65, s66, s24
	global_load_lds_dwordx4 v[80:81], off
	v_lshl_add_u64 v[80:81], v[198:199], 0, s[44:45]
	s_mov_b32 m0, s65
	s_nop 0
	global_load_lds_dwordx4 v[80:81], off
	v_lshl_add_u64 v[80:81], v[198:199], 0, s[48:49]
	s_add_i32 m0, s65, 0x2000
	s_nop 0
	global_load_lds_dwordx4 v[80:81], off
	v_lshl_add_u64 v[80:81], v[200:201], 0, s[40:41]
	s_mov_b32 m0, s46
	s_nop 0
	global_load_lds_dwordx4 v[80:81], off
	v_lshl_add_u64 v[80:81], v[200:201], 0, s[42:43]
	s_mov_b32 m0, s47
	s_nop 0
	global_load_lds_dwordx4 v[80:81], off
	s_waitcnt vmcnt(8)
	s_waitcnt lgkmcnt(0)
	s_barrier
	s_waitcnt lgkmcnt(0)
	v_mfma_f32_16x16x32_bf16 v[62:65], v[68:71], v[166:169], v[62:65]
	v_mfma_f32_16x16x32_bf16 v[58:61], v[76:79], v[166:169], v[58:61]
	v_mfma_f32_16x16x32_bf16 v[46:49], v[68:71], v[174:177], v[46:49]
	v_mfma_f32_16x16x32_bf16 v[42:45], v[76:79], v[174:177], v[42:45]
	s_add_i32 s64, s64, 2
	v_mfma_f32_16x16x32_bf16 v[30:33], v[68:71], v[182:185], v[30:33]
	s_add_u32 s28, s28, 0x80000
	v_mfma_f32_16x16x32_bf16 v[26:29], v[76:79], v[182:185], v[26:29]
	s_addc_u32 s29, s29, 0
	v_mfma_f32_16x16x32_bf16 v[14:17], v[68:71], v[190:193], v[14:17]
	s_add_u32 s76, s76, 0x800000
	v_mfma_f32_16x16x32_bf16 v[10:13], v[76:79], v[190:193], v[10:13]
	s_addc_u32 s77, s77, 0
	v_mfma_f32_16x16x32_bf16 v[62:65], v[72:75], v[170:173], v[62:65]
	s_cmp_gt_u32 s64, 29
	v_mfma_f32_16x16x32_bf16 v[58:61], v[138:141], v[170:173], v[58:61]
	v_mfma_f32_16x16x32_bf16 v[46:49], v[72:75], v[178:181], v[46:49]
	v_mfma_f32_16x16x32_bf16 v[42:45], v[138:141], v[178:181], v[42:45]
	v_mfma_f32_16x16x32_bf16 v[30:33], v[72:75], v[186:189], v[30:33]
	v_mfma_f32_16x16x32_bf16 v[26:29], v[138:141], v[186:189], v[26:29]
	v_mfma_f32_16x16x32_bf16 v[14:17], v[72:75], v[194:197], v[14:17]
	v_mfma_f32_16x16x32_bf16 v[10:13], v[138:141], v[194:197], v[10:13]
	v_mfma_f32_16x16x32_bf16 v[54:57], v[142:145], v[166:169], v[54:57]
	v_mfma_f32_16x16x32_bf16 v[50:53], v[158:161], v[166:169], v[50:53]
	v_mfma_f32_16x16x32_bf16 v[38:41], v[142:145], v[174:177], v[38:41]
	v_mfma_f32_16x16x32_bf16 v[34:37], v[158:161], v[174:177], v[34:37]
	v_mfma_f32_16x16x32_bf16 v[22:25], v[142:145], v[182:185], v[22:25]
	v_mfma_f32_16x16x32_bf16 v[18:21], v[158:161], v[182:185], v[18:21]
	v_mfma_f32_16x16x32_bf16 v[6:9], v[142:145], v[190:193], v[6:9]
	v_mfma_f32_16x16x32_bf16 v[2:5], v[158:161], v[190:193], v[2:5]
	v_mfma_f32_16x16x32_bf16 v[54:57], v[154:157], v[170:173], v[54:57]
	v_mfma_f32_16x16x32_bf16 v[50:53], v[162:165], v[170:173], v[50:53]
	v_mfma_f32_16x16x32_bf16 v[38:41], v[154:157], v[178:181], v[38:41]
	v_mfma_f32_16x16x32_bf16 v[34:37], v[162:165], v[178:181], v[34:37]
	v_mfma_f32_16x16x32_bf16 v[22:25], v[154:157], v[186:189], v[22:25]
	v_mfma_f32_16x16x32_bf16 v[18:21], v[162:165], v[186:189], v[18:21]
	v_mfma_f32_16x16x32_bf16 v[6:9], v[154:157], v[194:197], v[6:9]
	v_mfma_f32_16x16x32_bf16 v[2:5], v[162:165], v[194:197], v[2:5]
	s_barrier
	s_cbranch_scc0 .LBB0_707
; #define LAS __attribute__((address_space(3)))
; __device__ __forceinline__ f32x4 sigmoid4(f32x4 x) { return rcp_1p_exp2(x * -1.4426950409f); }
; #define G8_BAR __builtin_amdgcn_s_barrier()
; template <class P>
; __device__ __forceinline__ void gemm_phase(LAS unsigned char* lds, const P& p, const int G, const int c) {
;     ...
;         if (wr == 0) G8_BAR;
;     __device__ __forceinline__ void epi(Acc& acc, const Unit& u, int wr, int wc, int fr, int fq, LAS unsigned char*) const {
;         f32x4 b0[2], b1[2];
; #pragma unroll
;         for (int bj = 0; bj < 2; ++bj) { const int n0 = u.pn * 256 + bj * 128 + wc * 32 + 8 * fq; b0[bj] = *(const f32x4*)(bglu + n0); b1[bj] = *(const f32x4*)(bglu + n0 + 4); }
; #pragma unroll
;         for (int ai = 0; ai < 2; ++ai) {
;             u32x4 gv[4][2], sv[4][2];
; #pragma unroll
;             for (int m = 0; m < 4; ++m) { const int tok = u.pm * 256 + ai * 128 + wr * 64 + m * 16 + fr;
; #pragma unroll
;                 for (int bj = 0; bj < 2; ++bj) { const int n0 = u.pn * 256 + bj * 128 + wc * 32 + 8 * fq;
;                     gv[m][bj] = __builtin_nontemporal_load((const u32x4*)(Gin + (size_t)(n0 >> 4) * GPLANE + (size_t)tok * 32 + (n0 & 15) * 2));
;                     sv[m][bj] = __builtin_nontemporal_load((const u32x4*)(SZ + ((((size_t)(u.pm * 8 + u.pn) * 256 + (tok & 255)) * 256) + (n0 & 255)) * 2)); } }
; #pragma unroll
;             for (int m = 0; m < 4; ++m) { const int tok = u.pm * 256 + ai * 128 + wr * 64 + m * 16 + fr;
; #pragma unroll
;                 for (int bj = 0; bj < 2; ++bj) { const int n0 = u.pn * 256 + bj * 128 + wc * 32 + 8 * fq;
;                     const f32x4 v0 = acc[ai][bj][m][0] + b0[bj], v1 = acc[ai][bj][m][1] + b1[bj];
;                     const u32x4 gq = gv[m][bj], sq = sv[m][bj];
;                     const f32x4 o0 = bf4_lo(u32x2{gq.x, gq.y}) * bf4_lo(u32x2{sq.x, sq.y}) * sigmoid4(v0), o1 = bf4_lo(u32x2{gq.z, gq.w}) * bf4_lo(u32x2{sq.z, sq.w}) * sigmoid4(v1);
.LBB0_710:
	s_lshl_b32 s18, s57, 8
	s_or_b32 s18, s18, s30
	v_or_b32_e32 v138, s18, v228
	v_readlane_b32 s76, v253, 7
	v_ashrrev_i32_e32 v139, 31, v138
	v_readlane_b32 s86, v253, 17
	v_readlane_b32 s87, v253, 18
	s_lshl_b32 s19, s72, 3
	v_lshl_add_u32 v214, s72, 8, v1
	v_lshl_add_u64 v[70:71], v[138:139], 2, s[86:87]
	global_load_dwordx4 v[74:77], v[70:71], off offset:16
	global_load_dwordx4 v[78:81], v[70:71], off
	s_add_i32 s28, s19, s57
	v_ashrrev_i32_e32 v66, 4, v138
	v_readlane_b32 s77, v253, 8
	s_ashr_i32 s29, s28, 31
	v_ashrrev_i32_e32 v67, 31, v66
	v_ashrrev_i32_e32 v215, 31, v214
	s_lshl_b64 s[76:77], s[28:29], 16
	v_lshlrev_b64 v[216:217], 20, v[66:67]
	v_lshlrev_b64 v[66:67], 5, v[214:215]
	v_lshl_add_u64 v[140:141], v[210:211], 0, v[66:67]
	v_or_b32_e32 v139, s76, v208
	v_bitop3_b32 v235, s18, v233, v228 bitop3:0xc8
	v_mov_b32_e32 v143, s77
	v_lshl_add_u64 v[66:67], v[140:141], 0, v[216:217]
	v_or_b32_e32 v142, v139, v235
	global_load_dwordx4 v[238:241], v[66:67], off nt
	v_lshl_add_u64 v[66:67], v[142:143], 1, s[22:23]
	global_load_dwordx4 v[242:245], v[66:67], off nt
	s_nop 0
	global_load_dwordx4 v[66:69], v[70:71], off offset:528
	s_nop 0
	global_load_dwordx4 v[70:73], v[70:71], off offset:512
	v_or_b32_e32 v142, 0x80, v138
	v_ashrrev_i32_e32 v144, 4, v142
	v_ashrrev_i32_e32 v145, 31, v144
	s_movk_i32 s19, 0xf8
	v_lshlrev_b64 v[218:219], 20, v[144:145]
	v_bitop3_b32 v236, v138, s19, v234 bitop3:0xc8
	v_lshl_add_u64 v[140:141], v[140:141], 0, v[218:219]
	v_or_b32_e32 v142, v139, v236
	v_lshl_add_u64 v[138:139], v[142:143], 1, s[22:23]
	global_load_dwordx4 v[198:201], v[140:141], off nt
	global_load_dwordx4 v[194:197], v[138:139], off nt
	v_or_b32_e32 v226, 16, v214
	v_ashrrev_i32_e32 v227, 31, v226
	v_lshlrev_b32_e32 v140, 8, v226
	v_lshlrev_b64 v[138:139], 5, v[226:227]
	v_and_b32_e32 v140, 0xdf00, v140
	v_lshl_add_u64 v[138:139], v[210:211], 0, v[138:139]
	v_or_b32_e32 v144, s76, v140
	v_lshl_add_u64 v[140:141], v[138:139], 0, v[216:217]
	v_or_b32_e32 v220, v144, v235
	v_mov_b32_e32 v221, s77
	v_lshl_add_u64 v[142:143], v[220:221], 1, s[22:23]
	global_load_dwordx4 v[190:193], v[140:141], off nt
	global_load_dwordx4 v[186:189], v[142:143], off nt
	v_lshl_add_u64 v[138:139], v[138:139], 0, v[218:219]
	v_or_b32_e32 v220, v144, v236
	v_lshl_add_u64 v[140:141], v[220:221], 1, s[22:23]
	global_load_dwordx4 v[182:185], v[138:139], off nt
	global_load_dwordx4 v[178:181], v[140:141], off nt
	v_or_b32_e32 v224, 32, v214
	v_ashrrev_i32_e32 v225, 31, v224
	v_lshlrev_b32_e32 v140, 8, v224
	v_lshlrev_b64 v[138:139], 5, v[224:225]
	v_and_b32_e32 v140, 0xef00, v140
	v_lshl_add_u64 v[138:139], v[210:211], 0, v[138:139]
	v_or_b32_e32 v144, s76, v140
	v_lshl_add_u64 v[140:141], v[138:139], 0, v[216:217]
	v_or_b32_e32 v220, v144, v235
	v_lshl_add_u64 v[142:143], v[220:221], 1, s[22:23]
	global_load_dwordx4 v[174:177], v[140:141], off nt
	global_load_dwordx4 v[170:173], v[142:143], off nt
	v_lshl_add_u64 v[138:139], v[138:139], 0, v[218:219]
	v_or_b32_e32 v220, v144, v236
	v_lshl_add_u64 v[140:141], v[220:221], 1, s[22:23]
	global_load_dwordx4 v[166:169], v[138:139], off nt
	global_load_dwordx4 v[162:165], v[140:141], off nt
	v_or_b32_e32 v222, 48, v214
	v_ashrrev_i32_e32 v223, 31, v222
	v_lshlrev_b32_e32 v140, 8, v222
	v_lshlrev_b64 v[138:139], 5, v[222:223]
	v_and_b32_e32 v140, 0xff00, v140
	v_lshl_add_u64 v[138:139], v[210:211], 0, v[138:139]
	v_or_b32_e32 v144, s76, v140
	v_lshl_add_u64 v[140:141], v[138:139], 0, v[216:217]
	v_or_b32_e32 v220, v144, v235
	v_lshl_add_u64 v[142:143], v[220:221], 1, s[22:23]
	global_load_dwordx4 v[158:161], v[140:141], off nt
	global_load_dwordx4 v[154:157], v[142:143], off nt
	v_or_b32_e32 v220, v144, v236
	v_lshl_add_u64 v[138:139], v[138:139], 0, v[218:219]
	v_lshl_add_u64 v[140:141], v[220:221], 1, s[22:23]
	global_load_dwordx4 v[142:145], v[138:139], off nt
	s_nop 0
	global_load_dwordx4 v[138:141], v[140:141], off nt
	s_ashr_i32 s28, s18, 6
	s_ashr_i32 s29, s28, 31
	s_lshl_b64 s[18:19], s[28:29], 22
	s_cmp_lg_u64 s[52:53], 0
	s_cbranch_scc0 .Lalg_710
	s_barrier
.Lalg_710:
	s_waitcnt vmcnt(0)
	v_pk_add_f32 v[148:149], v[148:149], v[76:77]
	v_pk_add_f32 v[152:153], v[152:153], v[80:81]
	v_pk_add_f32 v[150:151], v[150:151], v[78:79]
	v_pk_mul_f32 v[152:153], v[152:153], s[56:57] op_sel_hi:[1,0]
	v_pk_add_f32 v[146:147], v[146:147], v[74:75]
	v_pk_mul_f32 v[150:151], v[150:151], s[56:57] op_sel_hi:[1,0]
	v_exp_f32_e32 v152, v152
	v_exp_f32_e32 v153, v153
	v_exp_f32_e32 v150, v150
	v_exp_f32_e32 v151, v151
	v_pk_mul_f32 v[148:149], v[148:149], s[56:57] op_sel_hi:[1,0]
	v_pk_mul_f32 v[146:147], v[146:147], s[56:57] op_sel_hi:[1,0]
	v_exp_f32_e32 v148, v148
	v_exp_f32_e32 v146, v146
	v_exp_f32_e32 v149, v149
	v_exp_f32_e32 v147, v147
	v_pk_add_f32 v[152:153], v[152:153], 1.0 op_sel_hi:[1,0]
	v_pk_add_f32 v[150:151], v[150:151], 1.0 op_sel_hi:[1,0]
	v_rcp_f32_e32 v152, v152
	v_rcp_f32_e32 v153, v153
	v_pk_add_f32 v[136:137], v[136:137], v[72:73]
	v_pk_add_f32 v[134:135], v[134:135], v[70:71]
	v_pk_mul_f32 v[136:137], v[136:137], s[56:57] op_sel_hi:[1,0]
	v_pk_mul_f32 v[134:135], v[134:135], s[56:57] op_sel_hi:[1,0]
	v_rcp_f32_e32 v150, v150
	v_rcp_f32_e32 v151, v151
	v_pk_add_f32 v[148:149], v[148:149], 1.0 op_sel_hi:[1,0]
	v_pk_add_f32 v[146:147], v[146:147], 1.0 op_sel_hi:[1,0]
	v_pk_add_f32 v[132:133], v[132:133], v[68:69]
	v_pk_add_f32 v[130:131], v[130:131], v[66:67]
	v_exp_f32_e32 v134, v134
	v_exp_f32_e32 v136, v136
	v_exp_f32_e32 v137, v137
	v_exp_f32_e32 v135, v135
	v_lshlrev_b32_e32 v248, 16, v238
	v_and_b32_e32 v249, 0xffff0000, v238
	v_lshlrev_b32_e32 v238, 16, v239
	v_and_b32_e32 v239, 0xffff0000, v239
; __device__ __forceinline__ f32x4 sigmoid4(f32x4 x) { return rcp_1p_exp2(x * -1.4426950409f); }
;     __device__ __forceinline__ void epi(Acc& acc, const Unit& u, int wr, int wc, int fr, int fq, LAS unsigned char*) const {
;     ...
;             for (int m = 0; m < 4; ++m) { const int tok = u.pm * 256 + ai * 128 + wr * 64 + m * 16 + fr;
; #pragma unroll
;                 for (int bj = 0; bj < 2; ++bj) { const int n0 = u.pn * 256 + bj * 128 + wc * 32 + 8 * fq;
;                     const f32x4 v0 = acc[ai][bj][m][0] + b0[bj], v1 = acc[ai][bj][m][1] + b1[bj];
;                     const u32x4 gq = gv[m][bj], sq = sv[m][bj];
;                     const f32x4 o0 = bf4_lo(u32x2{gq.x, gq.y}) * bf4_lo(u32x2{sq.x, sq.y}) * sigmoid4(v0), o1 = bf4_lo(u32x2{gq.z, gq.w}) * bf4_lo(u32x2{sq.z, sq.w}) * sigmoid4(v1);
;                     u32x4 w; w.x = pk2(o0[0], o0[1]); w.y = pk2(o0[2], o0[3]); w.z = pk2(o1[0], o1[1]); w.w = pk2(o1[2], o1[3]);
;                     *(u32x4*)(A4 + (size_t)(n0 >> 6) * A4PLANE + (size_t)tok * 128 + (n0 & 63) * 2) = w; } } }
	v_lshlrev_b32_e32 v250, 16, v242
	v_and_b32_e32 v251, 0xffff0000, v242
	v_lshlrev_b32_e32 v242, 16, v243
	v_and_b32_e32 v243, 0xffff0000, v243
	v_rcp_f32_e32 v146, v146
	v_rcp_f32_e32 v148, v148
	v_rcp_f32_e32 v149, v149
	v_rcp_f32_e32 v147, v147
	v_pk_mul_f32 v[132:133], v[132:133], s[56:57] op_sel_hi:[1,0]
	v_pk_mul_f32 v[130:131], v[130:131], s[56:57] op_sel_hi:[1,0]
	v_pk_mul_f32 v[238:239], v[238:239], v[242:243]
	v_exp_f32_e32 v130, v130
	v_exp_f32_e32 v132, v132
	v_exp_f32_e32 v133, v133
	v_exp_f32_e32 v131, v131
	v_pk_mul_f32 v[248:249], v[248:249], v[250:251]
	v_pk_mul_f32 v[152:153], v[238:239], v[152:153]
	v_lshlrev_b32_e32 v238, 16, v240
	v_and_b32_e32 v239, 0xffff0000, v240
	v_lshlrev_b32_e32 v240, 16, v241
	v_and_b32_e32 v241, 0xffff0000, v241
	v_lshlrev_b32_e32 v242, 16, v244
	v_and_b32_e32 v243, 0xffff0000, v244
	v_lshlrev_b32_e32 v244, 16, v245
	v_and_b32_e32 v245, 0xffff0000, v245
	s_add_u32 s72, s34, s18
	v_lshlrev_b64 v[246:247], 7, v[214:215]
	v_pk_mul_f32 v[150:151], v[248:249], v[150:151]
	v_pk_mul_f32 v[238:239], v[238:239], v[242:243]
	v_pk_mul_f32 v[240:241], v[240:241], v[244:245]
	s_addc_u32 s73, s35, s19
	v_pk_add_f32 v[136:137], v[136:137], 1.0 op_sel_hi:[1,0]
	v_pk_add_f32 v[134:135], v[134:135], 1.0 op_sel_hi:[1,0]
	v_pk_add_f32 v[128:129], v[128:129], v[80:81]
	v_pk_add_f32 v[126:127], v[126:127], v[78:79]
	v_pk_mul_f32 v[240:241], v[240:241], v[148:149]
	v_pk_mul_f32 v[148:149], v[238:239], v[146:147]
	v_cvt_pk_bf16_f32 v146, v150, v151
	v_lshl_add_u64 v[150:151], s[72:73], 0, v[246:247]
	v_rcp_f32_e32 v134, v134
	v_rcp_f32_e32 v136, v136
	v_rcp_f32_e32 v137, v137
	v_rcp_f32_e32 v135, v135
	v_pk_mul_f32 v[128:129], v[128:129], s[56:57] op_sel_hi:[1,0]
	v_pk_mul_f32 v[126:127], v[126:127], s[56:57] op_sel_hi:[1,0]
	v_cvt_pk_bf16_f32 v147, v152, v153
	v_cvt_pk_bf16_f32 v148, v148, v149
	v_cvt_pk_bf16_f32 v149, v240, v241
	v_lshl_add_u64 v[150:151], v[150:151], 0, v[206:207]
	v_pk_add_f32 v[132:133], v[132:133], 1.0 op_sel_hi:[1,0]
	v_pk_add_f32 v[130:131], v[130:131], 1.0 op_sel_hi:[1,0]
	s_or_b32 s18, s28, 2
	v_pk_add_f32 v[124:125], v[124:125], v[76:77]
	v_pk_add_f32 v[122:123], v[122:123], v[74:75]
	v_exp_f32_e32 v126, v126
	v_exp_f32_e32 v128, v128
	v_exp_f32_e32 v129, v129
	v_exp_f32_e32 v127, v127
	global_store_dwordx4 v[150:151], v[146:149], off
	v_lshlrev_b32_e32 v150, 16, v194
	v_and_b32_e32 v151, 0xffff0000, v194
	v_lshlrev_b32_e32 v146, 16, v198
	v_and_b32_e32 v147, 0xffff0000, v198
	v_lshlrev_b32_e32 v148, 16, v199
	v_and_b32_e32 v149, 0xffff0000, v199
	v_lshlrev_b32_e32 v152, 16, v195
	v_and_b32_e32 v153, 0xffff0000, v195
	v_rcp_f32_e32 v130, v130
	v_rcp_f32_e32 v132, v132
	v_rcp_f32_e32 v133, v133
	v_rcp_f32_e32 v131, v131
	s_ashr_i32 s19, s18, 31
	v_pk_mul_f32 v[124:125], v[124:125], s[56:57] op_sel_hi:[1,0]
	v_pk_mul_f32 v[122:123], v[122:123], s[56:57] op_sel_hi:[1,0]
	v_pk_mul_f32 v[146:147], v[146:147], v[150:151]
	v_pk_mul_f32 v[148:149], v[148:149], v[152:153]
	s_lshl_b64 s[18:19], s[18:19], 22
	v_exp_f32_e32 v122, v122
	v_exp_f32_e32 v124, v124
	v_exp_f32_e32 v125, v125
	v_exp_f32_e32 v123, v123
	v_pk_mul_f32 v[136:137], v[148:149], v[136:137]
	v_pk_mul_f32 v[134:135], v[146:147], v[134:135]
	v_lshlrev_b32_e32 v146, 16, v200
	v_and_b32_e32 v147, 0xffff0000, v200
	v_lshlrev_b32_e32 v148, 16, v201
	v_and_b32_e32 v149, 0xffff0000, v201
	v_lshlrev_b32_e32 v150, 16, v196
	v_and_b32_e32 v151, 0xffff0000, v196
	v_lshlrev_b32_e32 v152, 16, v197
	v_and_b32_e32 v153, 0xffff0000, v197
	s_add_u32 s74, s34, s18
	v_pk_mul_f32 v[146:147], v[146:147], v[150:151]
	v_pk_mul_f32 v[148:149], v[148:149], v[152:153]
	s_addc_u32 s75, s35, s19
	v_pk_add_f32 v[128:129], v[128:129], 1.0 op_sel_hi:[1,0]
	v_pk_add_f32 v[126:127], v[126:127], 1.0 op_sel_hi:[1,0]
	v_pk_add_f32 v[120:121], v[120:121], v[72:73]
	v_pk_add_f32 v[118:119], v[118:119], v[70:71]
	v_pk_mul_f32 v[148:149], v[148:149], v[132:133]
	v_pk_mul_f32 v[132:133], v[146:147], v[130:131]
	v_cvt_pk_bf16_f32 v130, v134, v135
	v_lshl_add_u64 v[134:135], s[74:75], 0, v[246:247]
	v_rcp_f32_e32 v126, v126
	v_rcp_f32_e32 v128, v128
	v_rcp_f32_e32 v129, v129
	v_rcp_f32_e32 v127, v127
	v_pk_mul_f32 v[120:121], v[120:121], s[56:57] op_sel_hi:[1,0]
	v_pk_mul_f32 v[118:119], v[118:119], s[56:57] op_sel_hi:[1,0]
	v_cvt_pk_bf16_f32 v131, v136, v137
	v_cvt_pk_bf16_f32 v132, v132, v133
	v_cvt_pk_bf16_f32 v133, v148, v149
	v_lshl_add_u64 v[134:135], v[134:135], 0, v[206:207]
	v_pk_add_f32 v[124:125], v[124:125], 1.0 op_sel_hi:[1,0]
	v_pk_add_f32 v[122:123], v[122:123], 1.0 op_sel_hi:[1,0]
	v_pk_add_f32 v[116:117], v[116:117], v[68:69]
	v_pk_add_f32 v[114:115], v[114:115], v[66:67]
	v_exp_f32_e32 v118, v118
	v_exp_f32_e32 v120, v120
	v_exp_f32_e32 v121, v121
	v_exp_f32_e32 v119, v119
	global_store_dwordx4 v[134:135], v[130:133], off
	v_lshlrev_b32_e32 v134, 16, v191
	v_and_b32_e32 v135, 0xffff0000, v191
	v_lshlrev_b32_e32 v132, 16, v190
	v_and_b32_e32 v133, 0xffff0000, v190
	v_lshlrev_b32_e32 v136, 16, v186
	v_and_b32_e32 v137, 0xffff0000, v186
	v_lshlrev_b32_e32 v146, 16, v187
	v_and_b32_e32 v147, 0xffff0000, v187
	v_rcp_f32_e32 v122, v122
	v_rcp_f32_e32 v124, v124
	v_rcp_f32_e32 v125, v125
	v_rcp_f32_e32 v123, v123
	v_pk_mul_f32 v[116:117], v[116:117], s[56:57] op_sel_hi:[1,0]
	v_pk_mul_f32 v[114:115], v[114:115], s[56:57] op_sel_hi:[1,0]
	v_pk_mul_f32 v[132:133], v[132:133], v[136:137]
	v_pk_mul_f32 v[134:135], v[134:135], v[146:147]
	v_exp_f32_e32 v114, v114
	v_exp_f32_e32 v116, v116
	v_exp_f32_e32 v117, v117
	v_exp_f32_e32 v115, v115
	v_pk_mul_f32 v[128:129], v[128:129], v[134:135]
	v_pk_mul_f32 v[126:127], v[126:127], v[132:133]
	v_lshlrev_b32_e32 v132, 16, v192
; __device__ __forceinline__ f32x4 sigmoid4(f32x4 x) { return rcp_1p_exp2(x * -1.4426950409f); }
;     __device__ __forceinline__ void epi(Acc& acc, const Unit& u, int wr, int wc, int fr, int fq, LAS unsigned char*) const {
;     ...
;             for (int m = 0; m < 4; ++m) { const int tok = u.pm * 256 + ai * 128 + wr * 64 + m * 16 + fr;
; #pragma unroll
;                 for (int bj = 0; bj < 2; ++bj) { const int n0 = u.pn * 256 + bj * 128 + wc * 32 + 8 * fq;
;                     const f32x4 v0 = acc[ai][bj][m][0] + b0[bj], v1 = acc[ai][bj][m][1] + b1[bj];
;                     const u32x4 gq = gv[m][bj], sq = sv[m][bj];
;                     const f32x4 o0 = bf4_lo(u32x2{gq.x, gq.y}) * bf4_lo(u32x2{sq.x, sq.y}) * sigmoid4(v0), o1 = bf4_lo(u32x2{gq.z, gq.w}) * bf4_lo(u32x2{sq.z, sq.w}) * sigmoid4(v1);
;                     u32x4 w; w.x = pk2(o0[0], o0[1]); w.y = pk2(o0[2], o0[3]); w.z = pk2(o1[0], o1[1]); w.w = pk2(o1[2], o1[3]);
;                     *(u32x4*)(A4 + (size_t)(n0 >> 6) * A4PLANE + (size_t)tok * 128 + (n0 & 63) * 2) = w; } } }
	v_and_b32_e32 v133, 0xffff0000, v192
	v_lshlrev_b32_e32 v134, 16, v193
	v_and_b32_e32 v135, 0xffff0000, v193
	v_lshlrev_b32_e32 v136, 16, v188
	v_and_b32_e32 v137, 0xffff0000, v188
	v_lshlrev_b32_e32 v146, 16, v189
	v_and_b32_e32 v147, 0xffff0000, v189
	v_lshlrev_b64 v[130:131], 7, v[226:227]
	v_pk_mul_f32 v[132:133], v[132:133], v[136:137]
	v_pk_mul_f32 v[134:135], v[134:135], v[146:147]
	v_pk_add_f32 v[120:121], v[120:121], 1.0 op_sel_hi:[1,0]
	v_pk_add_f32 v[118:119], v[118:119], 1.0 op_sel_hi:[1,0]
	v_pk_add_f32 v[112:113], v[112:113], v[80:81]
	v_pk_add_f32 v[110:111], v[110:111], v[78:79]
	v_pk_mul_f32 v[134:135], v[124:125], v[134:135]
	v_pk_mul_f32 v[124:125], v[122:123], v[132:133]
	v_cvt_pk_bf16_f32 v122, v126, v127
	v_lshl_add_u64 v[126:127], s[72:73], 0, v[130:131]
	v_rcp_f32_e32 v118, v118
	v_rcp_f32_e32 v120, v120
	v_rcp_f32_e32 v121, v121
	v_rcp_f32_e32 v119, v119
	v_pk_mul_f32 v[112:113], v[112:113], s[56:57] op_sel_hi:[1,0]
	v_pk_mul_f32 v[110:111], v[110:111], s[56:57] op_sel_hi:[1,0]
	v_cvt_pk_bf16_f32 v123, v128, v129
	v_cvt_pk_bf16_f32 v124, v124, v125
	v_cvt_pk_bf16_f32 v125, v134, v135
	v_lshl_add_u64 v[126:127], v[126:127], 0, v[206:207]
	v_pk_add_f32 v[116:117], v[116:117], 1.0 op_sel_hi:[1,0]
	v_pk_add_f32 v[114:115], v[114:115], 1.0 op_sel_hi:[1,0]
	v_pk_add_f32 v[108:109], v[108:109], v[76:77]
	v_pk_add_f32 v[106:107], v[106:107], v[74:75]
	v_exp_f32_e32 v110, v110
	v_exp_f32_e32 v112, v112
	v_exp_f32_e32 v113, v113
	v_exp_f32_e32 v111, v111
	global_store_dwordx4 v[126:127], v[122:125], off
	v_lshlrev_b32_e32 v126, 16, v178
	v_and_b32_e32 v127, 0xffff0000, v178
	v_lshlrev_b32_e32 v122, 16, v182
	v_and_b32_e32 v123, 0xffff0000, v182
	v_lshlrev_b32_e32 v124, 16, v183
	v_and_b32_e32 v125, 0xffff0000, v183
	v_lshlrev_b32_e32 v128, 16, v179
	v_and_b32_e32 v129, 0xffff0000, v179
	v_rcp_f32_e32 v114, v114
	v_rcp_f32_e32 v116, v116
	v_rcp_f32_e32 v117, v117
	v_rcp_f32_e32 v115, v115
	v_pk_mul_f32 v[108:109], v[108:109], s[56:57] op_sel_hi:[1,0]
	v_pk_mul_f32 v[106:107], v[106:107], s[56:57] op_sel_hi:[1,0]
	v_pk_mul_f32 v[122:123], v[122:123], v[126:127]
	v_pk_mul_f32 v[124:125], v[124:125], v[128:129]
	v_exp_f32_e32 v106, v106
	v_exp_f32_e32 v108, v108
	v_exp_f32_e32 v109, v109
	v_exp_f32_e32 v107, v107
	v_pk_mul_f32 v[120:121], v[120:121], v[124:125]
	v_pk_mul_f32 v[118:119], v[118:119], v[122:123]
	v_lshlrev_b32_e32 v122, 16, v184
	v_and_b32_e32 v123, 0xffff0000, v184
	v_lshlrev_b32_e32 v124, 16, v185
	v_and_b32_e32 v125, 0xffff0000, v185
	v_lshlrev_b32_e32 v126, 16, v180
	v_and_b32_e32 v127, 0xffff0000, v180
	v_lshlrev_b32_e32 v128, 16, v181
	v_and_b32_e32 v129, 0xffff0000, v181
	v_pk_mul_f32 v[122:123], v[122:123], v[126:127]
	v_pk_mul_f32 v[124:125], v[124:125], v[128:129]
	v_pk_add_f32 v[112:113], v[112:113], 1.0 op_sel_hi:[1,0]
	v_pk_add_f32 v[110:111], v[110:111], 1.0 op_sel_hi:[1,0]
	v_pk_add_f32 v[104:105], v[104:105], v[72:73]
	v_pk_add_f32 v[102:103], v[102:103], v[70:71]
	v_pk_mul_f32 v[124:125], v[116:117], v[124:125]
	v_pk_mul_f32 v[116:117], v[114:115], v[122:123]
	v_cvt_pk_bf16_f32 v114, v118, v119
	v_lshl_add_u64 v[118:119], s[74:75], 0, v[130:131]
	v_rcp_f32_e32 v110, v110
	v_rcp_f32_e32 v112, v112
	v_rcp_f32_e32 v113, v113
	v_rcp_f32_e32 v111, v111
	v_pk_mul_f32 v[104:105], v[104:105], s[56:57] op_sel_hi:[1,0]
	v_pk_mul_f32 v[102:103], v[102:103], s[56:57] op_sel_hi:[1,0]
	v_cvt_pk_bf16_f32 v115, v120, v121
	v_cvt_pk_bf16_f32 v116, v116, v117
	v_cvt_pk_bf16_f32 v117, v124, v125
	v_lshl_add_u64 v[118:119], v[118:119], 0, v[206:207]
	v_pk_add_f32 v[108:109], v[108:109], 1.0 op_sel_hi:[1,0]
	v_pk_add_f32 v[106:107], v[106:107], 1.0 op_sel_hi:[1,0]
	v_pk_add_f32 v[100:101], v[100:101], v[68:69]
	v_pk_add_f32 v[98:99], v[98:99], v[66:67]
	v_exp_f32_e32 v102, v102
	v_exp_f32_e32 v104, v104
	v_exp_f32_e32 v105, v105
	v_exp_f32_e32 v103, v103
	global_store_dwordx4 v[118:119], v[114:117], off
	v_lshlrev_b32_e32 v118, 16, v175
	v_and_b32_e32 v119, 0xffff0000, v175
	v_lshlrev_b32_e32 v116, 16, v174
	v_and_b32_e32 v117, 0xffff0000, v174
	v_lshlrev_b32_e32 v120, 16, v170
	v_and_b32_e32 v121, 0xffff0000, v170
	v_lshlrev_b32_e32 v122, 16, v171
	v_and_b32_e32 v123, 0xffff0000, v171
	v_rcp_f32_e32 v106, v106
	v_rcp_f32_e32 v108, v108
	v_rcp_f32_e32 v109, v109
	v_rcp_f32_e32 v107, v107
	v_pk_mul_f32 v[100:101], v[100:101], s[56:57] op_sel_hi:[1,0]
	v_pk_mul_f32 v[98:99], v[98:99], s[56:57] op_sel_hi:[1,0]
	v_pk_mul_f32 v[116:117], v[116:117], v[120:121]
	v_pk_mul_f32 v[118:119], v[118:119], v[122:123]
	v_exp_f32_e32 v98, v98
	v_exp_f32_e32 v100, v100
	v_exp_f32_e32 v101, v101
	v_exp_f32_e32 v99, v99
	v_pk_mul_f32 v[112:113], v[112:113], v[118:119]
	v_pk_mul_f32 v[110:111], v[110:111], v[116:117]
	v_lshlrev_b32_e32 v116, 16, v176
	v_and_b32_e32 v117, 0xffff0000, v176
	v_lshlrev_b32_e32 v118, 16, v177
	v_and_b32_e32 v119, 0xffff0000, v177
	v_lshlrev_b32_e32 v120, 16, v172
	v_and_b32_e32 v121, 0xffff0000, v172
	v_lshlrev_b32_e32 v122, 16, v173
	v_and_b32_e32 v123, 0xffff0000, v173
	v_lshlrev_b64 v[114:115], 7, v[224:225]
	v_pk_mul_f32 v[116:117], v[116:117], v[120:121]
	v_pk_mul_f32 v[118:119], v[118:119], v[122:123]
	v_pk_add_f32 v[104:105], v[104:105], 1.0 op_sel_hi:[1,0]
	v_pk_add_f32 v[102:103], v[102:103], 1.0 op_sel_hi:[1,0]
	v_pk_add_f32 v[96:97], v[96:97], v[80:81]
	v_pk_add_f32 v[94:95], v[94:95], v[78:79]
	v_pk_mul_f32 v[118:119], v[108:109], v[118:119]
	v_pk_mul_f32 v[108:109], v[106:107], v[116:117]
	v_cvt_pk_bf16_f32 v106, v110, v111
	v_lshl_add_u64 v[110:111], s[72:73], 0, v[114:115]
	v_rcp_f32_e32 v102, v102
	v_rcp_f32_e32 v104, v104
	v_rcp_f32_e32 v105, v105
	v_rcp_f32_e32 v103, v103
; __device__ __forceinline__ f32x4 sigmoid4(f32x4 x) { return rcp_1p_exp2(x * -1.4426950409f); }
;     __device__ __forceinline__ void epi(Acc& acc, const Unit& u, int wr, int wc, int fr, int fq, LAS unsigned char*) const {
;     ...
;             for (int m = 0; m < 4; ++m) { const int tok = u.pm * 256 + ai * 128 + wr * 64 + m * 16 + fr;
; #pragma unroll
;                 for (int bj = 0; bj < 2; ++bj) { const int n0 = u.pn * 256 + bj * 128 + wc * 32 + 8 * fq;
;                     const f32x4 v0 = acc[ai][bj][m][0] + b0[bj], v1 = acc[ai][bj][m][1] + b1[bj];
;                     const u32x4 gq = gv[m][bj], sq = sv[m][bj];
;                     const f32x4 o0 = bf4_lo(u32x2{gq.x, gq.y}) * bf4_lo(u32x2{sq.x, sq.y}) * sigmoid4(v0), o1 = bf4_lo(u32x2{gq.z, gq.w}) * bf4_lo(u32x2{sq.z, sq.w}) * sigmoid4(v1);
;                     u32x4 w; w.x = pk2(o0[0], o0[1]); w.y = pk2(o0[2], o0[3]); w.z = pk2(o1[0], o1[1]); w.w = pk2(o1[2], o1[3]);
;                     *(u32x4*)(A4 + (size_t)(n0 >> 6) * A4PLANE + (size_t)tok * 128 + (n0 & 63) * 2) = w; } } }
	v_pk_mul_f32 v[96:97], v[96:97], s[56:57] op_sel_hi:[1,0]
	v_pk_mul_f32 v[94:95], v[94:95], s[56:57] op_sel_hi:[1,0]
	v_cvt_pk_bf16_f32 v107, v112, v113
	v_cvt_pk_bf16_f32 v108, v108, v109
	v_cvt_pk_bf16_f32 v109, v118, v119
	v_lshl_add_u64 v[110:111], v[110:111], 0, v[206:207]
	v_pk_add_f32 v[100:101], v[100:101], 1.0 op_sel_hi:[1,0]
	v_pk_add_f32 v[98:99], v[98:99], 1.0 op_sel_hi:[1,0]
	v_pk_add_f32 v[92:93], v[92:93], v[76:77]
	v_pk_add_f32 v[90:91], v[90:91], v[74:75]
	v_exp_f32_e32 v94, v94
	v_exp_f32_e32 v96, v96
	v_exp_f32_e32 v97, v97
	v_exp_f32_e32 v95, v95
	global_store_dwordx4 v[110:111], v[106:109], off
	v_lshlrev_b32_e32 v110, 16, v162
	v_and_b32_e32 v111, 0xffff0000, v162
	v_lshlrev_b32_e32 v106, 16, v166
	v_and_b32_e32 v107, 0xffff0000, v166
	v_lshlrev_b32_e32 v108, 16, v167
	v_and_b32_e32 v109, 0xffff0000, v167
	v_lshlrev_b32_e32 v112, 16, v163
	v_and_b32_e32 v113, 0xffff0000, v163
	v_rcp_f32_e32 v98, v98
	v_rcp_f32_e32 v100, v100
	v_rcp_f32_e32 v101, v101
	v_rcp_f32_e32 v99, v99
	v_pk_mul_f32 v[92:93], v[92:93], s[56:57] op_sel_hi:[1,0]
	v_pk_mul_f32 v[90:91], v[90:91], s[56:57] op_sel_hi:[1,0]
	v_pk_mul_f32 v[106:107], v[106:107], v[110:111]
	v_pk_mul_f32 v[108:109], v[108:109], v[112:113]
	v_exp_f32_e32 v90, v90
	v_exp_f32_e32 v92, v92
	v_exp_f32_e32 v93, v93
	v_exp_f32_e32 v91, v91
	v_pk_mul_f32 v[104:105], v[104:105], v[108:109]
	v_pk_mul_f32 v[102:103], v[102:103], v[106:107]
	v_lshlrev_b32_e32 v106, 16, v168
	v_and_b32_e32 v107, 0xffff0000, v168
	v_lshlrev_b32_e32 v108, 16, v169
	v_and_b32_e32 v109, 0xffff0000, v169
	v_lshlrev_b32_e32 v110, 16, v164
	v_and_b32_e32 v111, 0xffff0000, v164
	v_lshlrev_b32_e32 v112, 16, v165
	v_and_b32_e32 v113, 0xffff0000, v165
	v_pk_mul_f32 v[106:107], v[106:107], v[110:111]
	v_pk_mul_f32 v[108:109], v[108:109], v[112:113]
	v_pk_add_f32 v[96:97], v[96:97], 1.0 op_sel_hi:[1,0]
	v_pk_add_f32 v[94:95], v[94:95], 1.0 op_sel_hi:[1,0]
	v_pk_add_f32 v[88:89], v[88:89], v[72:73]
	v_pk_add_f32 v[86:87], v[86:87], v[70:71]
	v_pk_mul_f32 v[108:109], v[100:101], v[108:109]
	v_pk_mul_f32 v[100:101], v[98:99], v[106:107]
	v_cvt_pk_bf16_f32 v98, v102, v103
	v_lshl_add_u64 v[102:103], s[74:75], 0, v[114:115]
	v_rcp_f32_e32 v94, v94
	v_rcp_f32_e32 v96, v96
	v_rcp_f32_e32 v97, v97
	v_rcp_f32_e32 v95, v95
	v_pk_mul_f32 v[88:89], v[88:89], s[56:57] op_sel_hi:[1,0]
	v_pk_mul_f32 v[86:87], v[86:87], s[56:57] op_sel_hi:[1,0]
	v_cvt_pk_bf16_f32 v99, v104, v105
	v_cvt_pk_bf16_f32 v100, v100, v101
	v_cvt_pk_bf16_f32 v101, v108, v109
	v_lshl_add_u64 v[102:103], v[102:103], 0, v[206:207]
	v_pk_add_f32 v[92:93], v[92:93], 1.0 op_sel_hi:[1,0]
	v_pk_add_f32 v[90:91], v[90:91], 1.0 op_sel_hi:[1,0]
	v_pk_add_f32 v[84:85], v[84:85], v[68:69]
	v_pk_add_f32 v[82:83], v[82:83], v[66:67]
	v_exp_f32_e32 v86, v86
	v_exp_f32_e32 v88, v88
	v_exp_f32_e32 v89, v89
	v_exp_f32_e32 v87, v87
	global_store_dwordx4 v[102:103], v[98:101], off
	v_lshlrev_b32_e32 v102, 16, v159
	v_and_b32_e32 v103, 0xffff0000, v159
	v_lshlrev_b32_e32 v100, 16, v158
	v_and_b32_e32 v101, 0xffff0000, v158
	v_lshlrev_b32_e32 v104, 16, v154
	v_and_b32_e32 v105, 0xffff0000, v154
	v_lshlrev_b32_e32 v106, 16, v155
	v_and_b32_e32 v107, 0xffff0000, v155
	v_rcp_f32_e32 v90, v90
	v_rcp_f32_e32 v92, v92
	v_rcp_f32_e32 v93, v93
	v_rcp_f32_e32 v91, v91
	v_pk_mul_f32 v[84:85], v[84:85], s[56:57] op_sel_hi:[1,0]
	v_pk_mul_f32 v[82:83], v[82:83], s[56:57] op_sel_hi:[1,0]
	v_pk_mul_f32 v[100:101], v[100:101], v[104:105]
	v_pk_mul_f32 v[102:103], v[102:103], v[106:107]
	v_exp_f32_e32 v82, v82
	v_exp_f32_e32 v84, v84
	v_exp_f32_e32 v85, v85
	v_exp_f32_e32 v83, v83
	v_pk_mul_f32 v[96:97], v[96:97], v[102:103]
	v_pk_mul_f32 v[94:95], v[94:95], v[100:101]
	v_lshlrev_b32_e32 v100, 16, v160
	v_and_b32_e32 v101, 0xffff0000, v160
	v_lshlrev_b32_e32 v102, 16, v161
	v_and_b32_e32 v103, 0xffff0000, v161
	v_lshlrev_b32_e32 v104, 16, v156
	v_and_b32_e32 v105, 0xffff0000, v156
	v_lshlrev_b32_e32 v106, 16, v157
	v_and_b32_e32 v107, 0xffff0000, v157
	v_lshlrev_b64 v[98:99], 7, v[222:223]
	v_pk_mul_f32 v[100:101], v[100:101], v[104:105]
	v_pk_mul_f32 v[102:103], v[102:103], v[106:107]
	v_pk_add_f32 v[88:89], v[88:89], 1.0 op_sel_hi:[1,0]
	v_pk_add_f32 v[86:87], v[86:87], 1.0 op_sel_hi:[1,0]
	v_pk_mul_f32 v[102:103], v[92:93], v[102:103]
	v_pk_mul_f32 v[92:93], v[90:91], v[100:101]
	v_cvt_pk_bf16_f32 v90, v94, v95
	v_lshl_add_u64 v[94:95], s[72:73], 0, v[98:99]
	v_rcp_f32_e32 v86, v86
	v_rcp_f32_e32 v88, v88
	v_rcp_f32_e32 v89, v89
	v_rcp_f32_e32 v87, v87
	v_cvt_pk_bf16_f32 v91, v96, v97
	v_cvt_pk_bf16_f32 v92, v92, v93
	v_cvt_pk_bf16_f32 v93, v102, v103
	v_lshl_add_u64 v[94:95], v[94:95], 0, v[206:207]
	v_pk_add_f32 v[84:85], v[84:85], 1.0 op_sel_hi:[1,0]
	v_pk_add_f32 v[82:83], v[82:83], 1.0 op_sel_hi:[1,0]
	global_store_dwordx4 v[94:95], v[90:93], off
	v_lshlrev_b32_e32 v94, 16, v138
	v_and_b32_e32 v95, 0xffff0000, v138
	v_lshlrev_b32_e32 v90, 16, v142
	v_and_b32_e32 v91, 0xffff0000, v142
	v_lshlrev_b32_e32 v92, 16, v143
	v_and_b32_e32 v93, 0xffff0000, v143
	v_lshlrev_b32_e32 v96, 16, v139
	v_and_b32_e32 v97, 0xffff0000, v139
	v_rcp_f32_e32 v82, v82
	v_rcp_f32_e32 v84, v84
	v_rcp_f32_e32 v85, v85
	v_rcp_f32_e32 v83, v83
	v_pk_mul_f32 v[90:91], v[90:91], v[94:95]
	v_pk_mul_f32 v[92:93], v[92:93], v[96:97]
	v_pk_mul_f32 v[86:87], v[86:87], v[90:91]
	v_pk_mul_f32 v[88:89], v[88:89], v[92:93]
	v_lshlrev_b32_e32 v90, 16, v144
	v_and_b32_e32 v91, 0xffff0000, v144
	v_lshlrev_b32_e32 v92, 16, v145
	v_and_b32_e32 v93, 0xffff0000, v145
	v_lshlrev_b32_e32 v94, 16, v140
	v_and_b32_e32 v95, 0xffff0000, v140
	v_lshlrev_b32_e32 v96, 16, v141
	v_and_b32_e32 v97, 0xffff0000, v141
; __device__ __forceinline__ f32x4 sigmoid4(f32x4 x) { return rcp_1p_exp2(x * -1.4426950409f); }
;     __device__ __forceinline__ void epi(Acc& acc, const Unit& u, int wr, int wc, int fr, int fq, LAS unsigned char*) const {
;     ...
;         for (int ai = 0; ai < 2; ++ai) {
;             u32x4 gv[4][2], sv[4][2];
; #pragma unroll
;             for (int m = 0; m < 4; ++m) { const int tok = u.pm * 256 + ai * 128 + wr * 64 + m * 16 + fr;
; #pragma unroll
;                 for (int bj = 0; bj < 2; ++bj) { const int n0 = u.pn * 256 + bj * 128 + wc * 32 + 8 * fq;
;                     gv[m][bj] = __builtin_nontemporal_load((const u32x4*)(Gin + (size_t)(n0 >> 4) * GPLANE + (size_t)tok * 32 + (n0 & 15) * 2));
;                     sv[m][bj] = __builtin_nontemporal_load((const u32x4*)(SZ + ((((size_t)(u.pm * 8 + u.pn) * 256 + (tok & 255)) * 256) + (n0 & 255)) * 2)); } }
; #pragma unroll
;             for (int m = 0; m < 4; ++m) { const int tok = u.pm * 256 + ai * 128 + wr * 64 + m * 16 + fr;
; #pragma unroll
;                 for (int bj = 0; bj < 2; ++bj) { const int n0 = u.pn * 256 + bj * 128 + wc * 32 + 8 * fq;
;                     const f32x4 v0 = acc[ai][bj][m][0] + b0[bj], v1 = acc[ai][bj][m][1] + b1[bj];
;                     const u32x4 gq = gv[m][bj], sq = sv[m][bj];
;                     const f32x4 o0 = bf4_lo(u32x2{gq.x, gq.y}) * bf4_lo(u32x2{sq.x, sq.y}) * sigmoid4(v0), o1 = bf4_lo(u32x2{gq.z, gq.w}) * bf4_lo(u32x2{sq.z, sq.w}) * sigmoid4(v1);
;                     u32x4 w; w.x = pk2(o0[0], o0[1]); w.y = pk2(o0[2], o0[3]); w.z = pk2(o1[0], o1[1]); w.w = pk2(o1[2], o1[3]);
;                     *(u32x4*)(A4 + (size_t)(n0 >> 6) * A4PLANE + (size_t)tok * 128 + (n0 & 63) * 2) = w; } } }
	v_pk_mul_f32 v[90:91], v[90:91], v[94:95]
	v_pk_mul_f32 v[92:93], v[92:93], v[96:97]
	v_add_u32_e32 v152, 0x80, v214
	v_pk_mul_f32 v[92:93], v[84:85], v[92:93]
	v_pk_mul_f32 v[84:85], v[82:83], v[90:91]
	v_cvt_pk_bf16_f32 v82, v86, v87
	v_lshl_add_u64 v[86:87], s[74:75], 0, v[98:99]
	v_cvt_pk_bf16_f32 v83, v88, v89
	v_cvt_pk_bf16_f32 v84, v84, v85
	v_cvt_pk_bf16_f32 v85, v92, v93
	v_lshl_add_u64 v[86:87], v[86:87], 0, v[206:207]
	global_store_dwordx4 v[86:87], v[82:85], off
	v_ashrrev_i32_e32 v153, 31, v152
	v_add_u32_e32 v138, 0x90, v214
	v_lshlrev_b32_e32 v84, 8, v152
	v_lshlrev_b64 v[82:83], 5, v[152:153]
	v_and_b32_e32 v86, 0xcf00, v84
	v_lshl_add_u64 v[82:83], v[210:211], 0, v[82:83]
	v_or_b32_e32 v86, s76, v86
	v_lshl_add_u64 v[84:85], v[82:83], 0, v[216:217]
	v_or_b32_e32 v220, v86, v235
	global_load_dwordx4 v[140:143], v[84:85], off nt
	v_lshl_add_u64 v[84:85], v[220:221], 1, s[22:23]
	global_load_dwordx4 v[144:147], v[84:85], off nt
	v_lshl_add_u64 v[82:83], v[82:83], 0, v[218:219]
	v_or_b32_e32 v220, v86, v236
	v_lshl_add_u64 v[84:85], v[220:221], 1, s[22:23]
	global_load_dwordx4 v[148:151], v[82:83], off nt
	global_load_dwordx4 v[130:133], v[84:85], off nt
	v_ashrrev_i32_e32 v139, 31, v138
	v_lshlrev_b32_e32 v84, 8, v138
	v_lshlrev_b64 v[82:83], 5, v[138:139]
	v_and_b32_e32 v84, 0xdf00, v84
	v_lshl_add_u64 v[82:83], v[210:211], 0, v[82:83]
	v_or_b32_e32 v88, s76, v84
	v_lshl_add_u64 v[84:85], v[82:83], 0, v[216:217]
	v_or_b32_e32 v220, v88, v235
	v_lshl_add_u64 v[86:87], v[220:221], 1, s[22:23]
	global_load_dwordx4 v[126:129], v[84:85], off nt
	global_load_dwordx4 v[122:125], v[86:87], off nt
	v_lshl_add_u64 v[82:83], v[82:83], 0, v[218:219]
	v_or_b32_e32 v220, v88, v236
	v_lshl_add_u64 v[84:85], v[220:221], 1, s[22:23]
	global_load_dwordx4 v[118:121], v[82:83], off nt
	global_load_dwordx4 v[114:117], v[84:85], off nt
	v_add_u32_e32 v136, 0xa0, v214
	v_ashrrev_i32_e32 v137, 31, v136
	v_lshlrev_b32_e32 v84, 8, v136
	v_lshlrev_b64 v[82:83], 5, v[136:137]
	v_and_b32_e32 v84, 0xef00, v84
	v_lshl_add_u64 v[82:83], v[210:211], 0, v[82:83]
	v_or_b32_e32 v88, s76, v84
	v_lshl_add_u64 v[84:85], v[82:83], 0, v[216:217]
	v_or_b32_e32 v220, v88, v235
	v_lshl_add_u64 v[86:87], v[220:221], 1, s[22:23]
	global_load_dwordx4 v[110:113], v[84:85], off nt
	global_load_dwordx4 v[106:109], v[86:87], off nt
	v_lshl_add_u64 v[82:83], v[82:83], 0, v[218:219]
	v_or_b32_e32 v220, v88, v236
	v_lshl_add_u64 v[84:85], v[220:221], 1, s[22:23]
	global_load_dwordx4 v[102:105], v[82:83], off nt
	global_load_dwordx4 v[98:101], v[84:85], off nt
	v_add_u32_e32 v134, 0xb0, v214
	v_ashrrev_i32_e32 v135, 31, v134
	v_lshlrev_b32_e32 v84, 8, v134
	v_lshlrev_b64 v[82:83], 5, v[134:135]
	v_and_b32_e32 v84, 0xff00, v84
	v_lshl_add_u64 v[82:83], v[210:211], 0, v[82:83]
	v_or_b32_e32 v88, s76, v84
	v_lshl_add_u64 v[84:85], v[82:83], 0, v[216:217]
	v_or_b32_e32 v220, v88, v235
	v_lshl_add_u64 v[86:87], v[220:221], 1, s[22:23]
	global_load_dwordx4 v[94:97], v[84:85], off nt
	global_load_dwordx4 v[90:93], v[86:87], off nt
	v_or_b32_e32 v220, v88, v236
	v_lshl_add_u64 v[82:83], v[82:83], 0, v[218:219]
	v_lshl_add_u64 v[84:85], v[220:221], 1, s[22:23]
	global_load_dwordx4 v[86:89], v[82:83], off nt
	s_nop 0
	global_load_dwordx4 v[82:85], v[84:85], off nt
	v_pk_add_f32 v[64:65], v[64:65], v[80:81]
	v_pk_add_f32 v[62:63], v[62:63], v[78:79]
	v_pk_mul_f32 v[64:65], v[64:65], s[56:57] op_sel_hi:[1,0]
	v_pk_add_f32 v[60:61], v[60:61], v[76:77]
	v_pk_add_f32 v[58:59], v[58:59], v[74:75]
	v_pk_mul_f32 v[62:63], v[62:63], s[56:57] op_sel_hi:[1,0]
	v_exp_f32_e32 v64, v64
	v_exp_f32_e32 v65, v65
	v_exp_f32_e32 v62, v62
	v_exp_f32_e32 v63, v63
	v_pk_mul_f32 v[60:61], v[60:61], s[56:57] op_sel_hi:[1,0]
	v_pk_mul_f32 v[58:59], v[58:59], s[56:57] op_sel_hi:[1,0]
	v_exp_f32_e32 v60, v60
	v_exp_f32_e32 v58, v58
	v_exp_f32_e32 v61, v61
	v_exp_f32_e32 v59, v59
	v_pk_add_f32 v[64:65], v[64:65], 1.0 op_sel_hi:[1,0]
	v_pk_add_f32 v[56:57], v[56:57], v[72:73]
	v_pk_add_f32 v[54:55], v[54:55], v[70:71]
	v_pk_add_f32 v[62:63], v[62:63], 1.0 op_sel_hi:[1,0]
	v_rcp_f32_e32 v64, v64
	v_rcp_f32_e32 v65, v65
	v_pk_mul_f32 v[56:57], v[56:57], s[56:57] op_sel_hi:[1,0]
	v_pk_mul_f32 v[54:55], v[54:55], s[56:57] op_sel_hi:[1,0]
	v_rcp_f32_e32 v62, v62
	v_rcp_f32_e32 v63, v63
	v_pk_add_f32 v[60:61], v[60:61], 1.0 op_sel_hi:[1,0]
	v_pk_add_f32 v[58:59], v[58:59], 1.0 op_sel_hi:[1,0]
	v_pk_add_f32 v[52:53], v[52:53], v[68:69]
	v_pk_add_f32 v[50:51], v[50:51], v[66:67]
	v_exp_f32_e32 v54, v54
	v_exp_f32_e32 v56, v56
	v_exp_f32_e32 v57, v57
	v_exp_f32_e32 v55, v55
	s_waitcnt vmcnt(15)
	v_lshlrev_b32_e32 v154, 16, v140
	v_and_b32_e32 v155, 0xffff0000, v140
	v_lshlrev_b32_e32 v140, 16, v141
	v_and_b32_e32 v141, 0xffff0000, v141
	s_waitcnt vmcnt(14)
; __device__ __forceinline__ f32x4 sigmoid4(f32x4 x) { return rcp_1p_exp2(x * -1.4426950409f); }
;     __device__ __forceinline__ void epi(Acc& acc, const Unit& u, int wr, int wc, int fr, int fq, LAS unsigned char*) const {
;     ...
;             for (int m = 0; m < 4; ++m) { const int tok = u.pm * 256 + ai * 128 + wr * 64 + m * 16 + fr;
; #pragma unroll
;                 for (int bj = 0; bj < 2; ++bj) { const int n0 = u.pn * 256 + bj * 128 + wc * 32 + 8 * fq;
;                     const f32x4 v0 = acc[ai][bj][m][0] + b0[bj], v1 = acc[ai][bj][m][1] + b1[bj];
;                     const u32x4 gq = gv[m][bj], sq = sv[m][bj];
;                     const f32x4 o0 = bf4_lo(u32x2{gq.x, gq.y}) * bf4_lo(u32x2{sq.x, sq.y}) * sigmoid4(v0), o1 = bf4_lo(u32x2{gq.z, gq.w}) * bf4_lo(u32x2{sq.z, sq.w}) * sigmoid4(v1);
;                     u32x4 w; w.x = pk2(o0[0], o0[1]); w.y = pk2(o0[2], o0[3]); w.z = pk2(o1[0], o1[1]); w.w = pk2(o1[2], o1[3]);
;                     *(u32x4*)(A4 + (size_t)(n0 >> 6) * A4PLANE + (size_t)tok * 128 + (n0 & 63) * 2) = w; } } }
	v_lshlrev_b32_e32 v156, 16, v144
	v_and_b32_e32 v157, 0xffff0000, v144
	v_lshlrev_b32_e32 v144, 16, v145
	v_and_b32_e32 v145, 0xffff0000, v145
	v_rcp_f32_e32 v58, v58
	v_rcp_f32_e32 v60, v60
	v_rcp_f32_e32 v61, v61
	v_rcp_f32_e32 v59, v59
	v_pk_mul_f32 v[52:53], v[52:53], s[56:57] op_sel_hi:[1,0]
	v_pk_mul_f32 v[50:51], v[50:51], s[56:57] op_sel_hi:[1,0]
	v_pk_mul_f32 v[140:141], v[140:141], v[144:145]
	v_exp_f32_e32 v50, v50
	v_exp_f32_e32 v52, v52
	v_exp_f32_e32 v53, v53
	v_exp_f32_e32 v51, v51
	v_pk_mul_f32 v[154:155], v[154:155], v[156:157]
	v_pk_mul_f32 v[64:65], v[64:65], v[140:141]
	v_lshlrev_b32_e32 v140, 16, v142
	v_and_b32_e32 v141, 0xffff0000, v142
	v_lshlrev_b32_e32 v142, 16, v143
	v_and_b32_e32 v143, 0xffff0000, v143
	v_lshlrev_b32_e32 v144, 16, v146
	v_and_b32_e32 v145, 0xffff0000, v146
	v_lshlrev_b32_e32 v146, 16, v147
	v_and_b32_e32 v147, 0xffff0000, v147
	v_lshlrev_b64 v[152:153], 7, v[152:153]
	v_pk_mul_f32 v[62:63], v[62:63], v[154:155]
	v_pk_mul_f32 v[140:141], v[140:141], v[144:145]
	v_pk_mul_f32 v[142:143], v[142:143], v[146:147]
	v_pk_add_f32 v[56:57], v[56:57], 1.0 op_sel_hi:[1,0]
	v_pk_add_f32 v[54:55], v[54:55], 1.0 op_sel_hi:[1,0]
	v_pk_add_f32 v[48:49], v[48:49], v[80:81]
	v_pk_add_f32 v[46:47], v[46:47], v[78:79]
	v_pk_mul_f32 v[142:143], v[60:61], v[142:143]
	v_pk_mul_f32 v[60:61], v[58:59], v[140:141]
	v_cvt_pk_bf16_f32 v58, v62, v63
	v_lshl_add_u64 v[62:63], s[72:73], 0, v[152:153]
	v_rcp_f32_e32 v54, v54
	v_rcp_f32_e32 v56, v56
	v_rcp_f32_e32 v57, v57
	v_rcp_f32_e32 v55, v55
	v_pk_mul_f32 v[48:49], v[48:49], s[56:57] op_sel_hi:[1,0]
	v_pk_mul_f32 v[46:47], v[46:47], s[56:57] op_sel_hi:[1,0]
	v_cvt_pk_bf16_f32 v59, v64, v65
	v_cvt_pk_bf16_f32 v60, v60, v61
	v_cvt_pk_bf16_f32 v61, v142, v143
	v_lshl_add_u64 v[62:63], v[62:63], 0, v[206:207]
	v_pk_add_f32 v[52:53], v[52:53], 1.0 op_sel_hi:[1,0]
	v_pk_add_f32 v[50:51], v[50:51], 1.0 op_sel_hi:[1,0]
	v_pk_add_f32 v[44:45], v[44:45], v[76:77]
	v_pk_add_f32 v[42:43], v[42:43], v[74:75]
	v_exp_f32_e32 v46, v46
	v_exp_f32_e32 v48, v48
	v_exp_f32_e32 v49, v49
	v_exp_f32_e32 v47, v47
	global_store_dwordx4 v[62:63], v[58:61], off
	s_waitcnt vmcnt(13)
	v_lshlrev_b32_e32 v62, 16, v130
	v_and_b32_e32 v63, 0xffff0000, v130
	v_lshlrev_b32_e32 v58, 16, v148
	v_and_b32_e32 v59, 0xffff0000, v148
	v_lshlrev_b32_e32 v60, 16, v149
	v_and_b32_e32 v61, 0xffff0000, v149
	v_lshlrev_b32_e32 v64, 16, v131
	v_and_b32_e32 v65, 0xffff0000, v131
	v_rcp_f32_e32 v50, v50
	v_rcp_f32_e32 v52, v52
	v_rcp_f32_e32 v53, v53
	v_rcp_f32_e32 v51, v51
	v_pk_mul_f32 v[44:45], v[44:45], s[56:57] op_sel_hi:[1,0]
	v_pk_mul_f32 v[42:43], v[42:43], s[56:57] op_sel_hi:[1,0]
	v_pk_mul_f32 v[58:59], v[58:59], v[62:63]
	v_pk_mul_f32 v[60:61], v[60:61], v[64:65]
	v_exp_f32_e32 v42, v42
	v_exp_f32_e32 v44, v44
	v_exp_f32_e32 v45, v45
	v_exp_f32_e32 v43, v43
	v_pk_mul_f32 v[56:57], v[56:57], v[60:61]
	v_pk_mul_f32 v[54:55], v[54:55], v[58:59]
	v_lshlrev_b32_e32 v58, 16, v150
	v_and_b32_e32 v59, 0xffff0000, v150
	v_lshlrev_b32_e32 v60, 16, v151
	v_and_b32_e32 v61, 0xffff0000, v151
	v_lshlrev_b32_e32 v62, 16, v132
	v_and_b32_e32 v63, 0xffff0000, v132
	v_lshlrev_b32_e32 v64, 16, v133
	v_and_b32_e32 v65, 0xffff0000, v133
	v_pk_mul_f32 v[58:59], v[58:59], v[62:63]
	v_pk_mul_f32 v[60:61], v[60:61], v[64:65]
	v_pk_add_f32 v[48:49], v[48:49], 1.0 op_sel_hi:[1,0]
	v_pk_add_f32 v[46:47], v[46:47], 1.0 op_sel_hi:[1,0]
	v_pk_add_f32 v[40:41], v[40:41], v[72:73]
	v_pk_add_f32 v[38:39], v[38:39], v[70:71]
	v_pk_mul_f32 v[60:61], v[52:53], v[60:61]
	v_pk_mul_f32 v[52:53], v[50:51], v[58:59]
	v_cvt_pk_bf16_f32 v50, v54, v55
	v_lshl_add_u64 v[54:55], s[74:75], 0, v[152:153]
	v_rcp_f32_e32 v46, v46
	v_rcp_f32_e32 v48, v48
	v_rcp_f32_e32 v49, v49
	v_rcp_f32_e32 v47, v47
	v_pk_mul_f32 v[40:41], v[40:41], s[56:57] op_sel_hi:[1,0]
	v_pk_mul_f32 v[38:39], v[38:39], s[56:57] op_sel_hi:[1,0]
	v_cvt_pk_bf16_f32 v51, v56, v57
	v_cvt_pk_bf16_f32 v52, v52, v53
	v_cvt_pk_bf16_f32 v53, v60, v61
	v_lshl_add_u64 v[54:55], v[54:55], 0, v[206:207]
	v_pk_add_f32 v[44:45], v[44:45], 1.0 op_sel_hi:[1,0]
	v_pk_add_f32 v[42:43], v[42:43], 1.0 op_sel_hi:[1,0]
	v_pk_add_f32 v[36:37], v[36:37], v[68:69]
	v_pk_add_f32 v[34:35], v[34:35], v[66:67]
	v_exp_f32_e32 v38, v38
	v_exp_f32_e32 v40, v40
	v_exp_f32_e32 v41, v41
	v_exp_f32_e32 v39, v39
	global_store_dwordx4 v[54:55], v[50:53], off
	s_waitcnt vmcnt(13)
	v_lshlrev_b32_e32 v54, 16, v127
	v_and_b32_e32 v55, 0xffff0000, v127
	v_lshlrev_b32_e32 v52, 16, v126
	v_and_b32_e32 v53, 0xffff0000, v126
	s_waitcnt vmcnt(12)
	v_lshlrev_b32_e32 v56, 16, v122
	v_and_b32_e32 v57, 0xffff0000, v122
	v_lshlrev_b32_e32 v58, 16, v123
	v_and_b32_e32 v59, 0xffff0000, v123
	v_rcp_f32_e32 v42, v42
	v_rcp_f32_e32 v44, v44
	v_rcp_f32_e32 v45, v45
	v_rcp_f32_e32 v43, v43
	v_pk_mul_f32 v[36:37], v[36:37], s[56:57] op_sel_hi:[1,0]
	v_pk_mul_f32 v[34:35], v[34:35], s[56:57] op_sel_hi:[1,0]
	v_pk_mul_f32 v[52:53], v[52:53], v[56:57]
	v_pk_mul_f32 v[54:55], v[54:55], v[58:59]
	v_exp_f32_e32 v34, v34
	v_exp_f32_e32 v36, v36
	v_exp_f32_e32 v37, v37
	v_exp_f32_e32 v35, v35
	v_pk_mul_f32 v[48:49], v[48:49], v[54:55]
	v_pk_mul_f32 v[46:47], v[46:47], v[52:53]
	v_lshlrev_b32_e32 v52, 16, v128
	v_and_b32_e32 v53, 0xffff0000, v128
	v_lshlrev_b32_e32 v54, 16, v129
	v_and_b32_e32 v55, 0xffff0000, v129
	v_lshlrev_b32_e32 v56, 16, v124
	v_and_b32_e32 v57, 0xffff0000, v124
	v_lshlrev_b32_e32 v58, 16, v125
	v_and_b32_e32 v59, 0xffff0000, v125
	v_lshlrev_b64 v[50:51], 7, v[138:139]
	v_pk_mul_f32 v[52:53], v[52:53], v[56:57]
	v_pk_mul_f32 v[54:55], v[54:55], v[58:59]
	v_pk_add_f32 v[40:41], v[40:41], 1.0 op_sel_hi:[1,0]
	v_pk_add_f32 v[38:39], v[38:39], 1.0 op_sel_hi:[1,0]
	v_pk_add_f32 v[32:33], v[32:33], v[80:81]
	v_pk_add_f32 v[30:31], v[30:31], v[78:79]
	v_pk_mul_f32 v[54:55], v[44:45], v[54:55]
	v_pk_mul_f32 v[44:45], v[42:43], v[52:53]
	v_cvt_pk_bf16_f32 v42, v46, v47
	v_lshl_add_u64 v[46:47], s[72:73], 0, v[50:51]
	v_rcp_f32_e32 v38, v38
	v_rcp_f32_e32 v40, v40
	v_rcp_f32_e32 v41, v41
	v_rcp_f32_e32 v39, v39
	v_pk_mul_f32 v[32:33], v[32:33], s[56:57] op_sel_hi:[1,0]
	v_pk_mul_f32 v[30:31], v[30:31], s[56:57] op_sel_hi:[1,0]
	v_cvt_pk_bf16_f32 v43, v48, v49
	v_cvt_pk_bf16_f32 v44, v44, v45
	v_cvt_pk_bf16_f32 v45, v54, v55
	v_lshl_add_u64 v[46:47], v[46:47], 0, v[206:207]
	v_pk_add_f32 v[36:37], v[36:37], 1.0 op_sel_hi:[1,0]
	v_pk_add_f32 v[34:35], v[34:35], 1.0 op_sel_hi:[1,0]
	v_pk_add_f32 v[28:29], v[28:29], v[76:77]
	v_pk_add_f32 v[26:27], v[26:27], v[74:75]
	v_exp_f32_e32 v30, v30
	v_exp_f32_e32 v32, v32
	v_exp_f32_e32 v33, v33
	v_exp_f32_e32 v31, v31
	global_store_dwordx4 v[46:47], v[42:45], off
	s_waitcnt vmcnt(11)
; __device__ __forceinline__ f32x4 sigmoid4(f32x4 x) { return rcp_1p_exp2(x * -1.4426950409f); }
;     __device__ __forceinline__ void epi(Acc& acc, const Unit& u, int wr, int wc, int fr, int fq, LAS unsigned char*) const {
;     ...
;             for (int m = 0; m < 4; ++m) { const int tok = u.pm * 256 + ai * 128 + wr * 64 + m * 16 + fr;
; #pragma unroll
;                 for (int bj = 0; bj < 2; ++bj) { const int n0 = u.pn * 256 + bj * 128 + wc * 32 + 8 * fq;
;                     const f32x4 v0 = acc[ai][bj][m][0] + b0[bj], v1 = acc[ai][bj][m][1] + b1[bj];
;                     const u32x4 gq = gv[m][bj], sq = sv[m][bj];
;                     const f32x4 o0 = bf4_lo(u32x2{gq.x, gq.y}) * bf4_lo(u32x2{sq.x, sq.y}) * sigmoid4(v0), o1 = bf4_lo(u32x2{gq.z, gq.w}) * bf4_lo(u32x2{sq.z, sq.w}) * sigmoid4(v1);
;                     u32x4 w; w.x = pk2(o0[0], o0[1]); w.y = pk2(o0[2], o0[3]); w.z = pk2(o1[0], o1[1]); w.w = pk2(o1[2], o1[3]);
;                     *(u32x4*)(A4 + (size_t)(n0 >> 6) * A4PLANE + (size_t)tok * 128 + (n0 & 63) * 2) = w; } } }
	v_lshlrev_b32_e32 v46, 16, v114
	v_and_b32_e32 v47, 0xffff0000, v114
	v_lshlrev_b32_e32 v42, 16, v118
	v_and_b32_e32 v43, 0xffff0000, v118
	v_lshlrev_b32_e32 v44, 16, v119
	v_and_b32_e32 v45, 0xffff0000, v119
	v_lshlrev_b32_e32 v48, 16, v115
	v_and_b32_e32 v49, 0xffff0000, v115
	v_rcp_f32_e32 v34, v34
	v_rcp_f32_e32 v36, v36
	v_rcp_f32_e32 v37, v37
	v_rcp_f32_e32 v35, v35
	v_pk_mul_f32 v[28:29], v[28:29], s[56:57] op_sel_hi:[1,0]
	v_pk_mul_f32 v[26:27], v[26:27], s[56:57] op_sel_hi:[1,0]
	v_pk_mul_f32 v[42:43], v[42:43], v[46:47]
	v_pk_mul_f32 v[44:45], v[44:45], v[48:49]
	v_exp_f32_e32 v26, v26
	v_exp_f32_e32 v28, v28
	v_exp_f32_e32 v29, v29
	v_exp_f32_e32 v27, v27
	v_pk_mul_f32 v[40:41], v[40:41], v[44:45]
	v_pk_mul_f32 v[38:39], v[38:39], v[42:43]
	v_lshlrev_b32_e32 v42, 16, v120
	v_and_b32_e32 v43, 0xffff0000, v120
	v_lshlrev_b32_e32 v44, 16, v121
	v_and_b32_e32 v45, 0xffff0000, v121
	v_lshlrev_b32_e32 v46, 16, v116
	v_and_b32_e32 v47, 0xffff0000, v116
	v_lshlrev_b32_e32 v48, 16, v117
	v_and_b32_e32 v49, 0xffff0000, v117
	v_pk_mul_f32 v[42:43], v[42:43], v[46:47]
	v_pk_mul_f32 v[44:45], v[44:45], v[48:49]
	v_pk_add_f32 v[32:33], v[32:33], 1.0 op_sel_hi:[1,0]
	v_pk_add_f32 v[30:31], v[30:31], 1.0 op_sel_hi:[1,0]
	v_pk_add_f32 v[24:25], v[24:25], v[72:73]
	v_pk_add_f32 v[22:23], v[22:23], v[70:71]
	v_pk_mul_f32 v[44:45], v[36:37], v[44:45]
	v_pk_mul_f32 v[36:37], v[34:35], v[42:43]
	v_cvt_pk_bf16_f32 v34, v38, v39
	v_lshl_add_u64 v[38:39], s[74:75], 0, v[50:51]
	v_rcp_f32_e32 v30, v30
	v_rcp_f32_e32 v32, v32
	v_rcp_f32_e32 v33, v33
	v_rcp_f32_e32 v31, v31
	v_pk_mul_f32 v[24:25], v[24:25], s[56:57] op_sel_hi:[1,0]
	v_pk_mul_f32 v[22:23], v[22:23], s[56:57] op_sel_hi:[1,0]
	v_cvt_pk_bf16_f32 v35, v40, v41
	v_cvt_pk_bf16_f32 v36, v36, v37
	v_cvt_pk_bf16_f32 v37, v44, v45
	v_lshl_add_u64 v[38:39], v[38:39], 0, v[206:207]
	v_pk_add_f32 v[28:29], v[28:29], 1.0 op_sel_hi:[1,0]
	v_pk_add_f32 v[26:27], v[26:27], 1.0 op_sel_hi:[1,0]
	v_pk_add_f32 v[20:21], v[20:21], v[68:69]
	v_pk_add_f32 v[18:19], v[18:19], v[66:67]
	v_exp_f32_e32 v22, v22
	v_exp_f32_e32 v24, v24
	v_exp_f32_e32 v25, v25
	v_exp_f32_e32 v23, v23
	global_store_dwordx4 v[38:39], v[34:37], off
	s_waitcnt vmcnt(11)
	v_lshlrev_b32_e32 v38, 16, v111
	v_and_b32_e32 v39, 0xffff0000, v111
	v_lshlrev_b32_e32 v36, 16, v110
	v_and_b32_e32 v37, 0xffff0000, v110
	s_waitcnt vmcnt(10)
	v_lshlrev_b32_e32 v40, 16, v106
	v_and_b32_e32 v41, 0xffff0000, v106
	v_lshlrev_b32_e32 v42, 16, v107
	v_and_b32_e32 v43, 0xffff0000, v107
	v_rcp_f32_e32 v26, v26
	v_rcp_f32_e32 v28, v28
	v_rcp_f32_e32 v29, v29
	v_rcp_f32_e32 v27, v27
	v_pk_mul_f32 v[20:21], v[20:21], s[56:57] op_sel_hi:[1,0]
	v_pk_mul_f32 v[18:19], v[18:19], s[56:57] op_sel_hi:[1,0]
	v_pk_mul_f32 v[36:37], v[36:37], v[40:41]
	v_pk_mul_f32 v[38:39], v[38:39], v[42:43]
	v_exp_f32_e32 v18, v18
	v_exp_f32_e32 v20, v20
	v_exp_f32_e32 v21, v21
	v_exp_f32_e32 v19, v19
	v_pk_mul_f32 v[32:33], v[32:33], v[38:39]
	v_pk_mul_f32 v[30:31], v[30:31], v[36:37]
	v_lshlrev_b32_e32 v36, 16, v112
	v_and_b32_e32 v37, 0xffff0000, v112
	v_lshlrev_b32_e32 v38, 16, v113
	v_and_b32_e32 v39, 0xffff0000, v113
	v_lshlrev_b32_e32 v40, 16, v108
	v_and_b32_e32 v41, 0xffff0000, v108
	v_lshlrev_b32_e32 v42, 16, v109
	v_and_b32_e32 v43, 0xffff0000, v109
	v_lshlrev_b64 v[34:35], 7, v[136:137]
	v_pk_mul_f32 v[36:37], v[36:37], v[40:41]
	v_pk_mul_f32 v[38:39], v[38:39], v[42:43]
	v_pk_add_f32 v[24:25], v[24:25], 1.0 op_sel_hi:[1,0]
	v_pk_add_f32 v[22:23], v[22:23], 1.0 op_sel_hi:[1,0]
	v_pk_add_f32 v[16:17], v[16:17], v[80:81]
	v_pk_add_f32 v[14:15], v[14:15], v[78:79]
	v_pk_mul_f32 v[38:39], v[28:29], v[38:39]
	v_pk_mul_f32 v[28:29], v[26:27], v[36:37]
	v_cvt_pk_bf16_f32 v26, v30, v31
	v_lshl_add_u64 v[30:31], s[72:73], 0, v[34:35]
	v_rcp_f32_e32 v22, v22
	v_rcp_f32_e32 v24, v24
	v_rcp_f32_e32 v25, v25
	v_rcp_f32_e32 v23, v23
	v_pk_mul_f32 v[16:17], v[16:17], s[56:57] op_sel_hi:[1,0]
	v_pk_mul_f32 v[14:15], v[14:15], s[56:57] op_sel_hi:[1,0]
	v_cvt_pk_bf16_f32 v27, v32, v33
	v_cvt_pk_bf16_f32 v28, v28, v29
	v_cvt_pk_bf16_f32 v29, v38, v39
	v_lshl_add_u64 v[30:31], v[30:31], 0, v[206:207]
	v_pk_add_f32 v[20:21], v[20:21], 1.0 op_sel_hi:[1,0]
	v_pk_add_f32 v[18:19], v[18:19], 1.0 op_sel_hi:[1,0]
	v_pk_add_f32 v[12:13], v[12:13], v[76:77]
	v_pk_add_f32 v[10:11], v[10:11], v[74:75]
	v_exp_f32_e32 v14, v14
	v_exp_f32_e32 v16, v16
	v_exp_f32_e32 v17, v17
	v_exp_f32_e32 v15, v15
	global_store_dwordx4 v[30:31], v[26:29], off
	s_waitcnt vmcnt(9)
; __device__ __forceinline__ f32x4 sigmoid4(f32x4 x) { return rcp_1p_exp2(x * -1.4426950409f); }
; #define G8_BAR __builtin_amdgcn_s_barrier()
; template <class P>
; __device__ __forceinline__ void gemm_phase(LAS unsigned char* lds, const P& p, const int G, const int c) {
;     ...
;         if (!has_next) break;
; #pragma unroll
;         for (int a = 0; a < 2; ++a)
; #pragma unroll
;             for (int b = 0; b < 2; ++b)
; #pragma unroll
;                 for (int m = 0; m < 4; ++m)
; #pragma unroll
;                     for (int n = 0; n < 2; ++n) acc[a][b][m][n] = (f32x4){0.f, 0.f, 0.f, 0.f};
;         cur = nxt; ++ui; cA0 = nA0; cA1 = nA1; cB0 = nB0; cB1 = nB1;
;         if (wr == 1) G8_BAR;
;     __device__ __forceinline__ void epi(Acc& acc, const Unit& u, int wr, int wc, int fr, int fq, LAS unsigned char*) const {
;     ...
;             for (int m = 0; m < 4; ++m) { const int tok = u.pm * 256 + ai * 128 + wr * 64 + m * 16 + fr;
; #pragma unroll
;                 for (int bj = 0; bj < 2; ++bj) { const int n0 = u.pn * 256 + bj * 128 + wc * 32 + 8 * fq;
;                     const f32x4 v0 = acc[ai][bj][m][0] + b0[bj], v1 = acc[ai][bj][m][1] + b1[bj];
;                     const u32x4 gq = gv[m][bj], sq = sv[m][bj];
;                     const f32x4 o0 = bf4_lo(u32x2{gq.x, gq.y}) * bf4_lo(u32x2{sq.x, sq.y}) * sigmoid4(v0), o1 = bf4_lo(u32x2{gq.z, gq.w}) * bf4_lo(u32x2{sq.z, sq.w}) * sigmoid4(v1);
;                     u32x4 w; w.x = pk2(o0[0], o0[1]); w.y = pk2(o0[2], o0[3]); w.z = pk2(o1[0], o1[1]); w.w = pk2(o1[2], o1[3]);
;                     *(u32x4*)(A4 + (size_t)(n0 >> 6) * A4PLANE + (size_t)tok * 128 + (n0 & 63) * 2) = w; } } }
	v_lshlrev_b32_e32 v30, 16, v98
	v_and_b32_e32 v31, 0xffff0000, v98
	v_lshlrev_b32_e32 v26, 16, v102
	v_and_b32_e32 v27, 0xffff0000, v102
	v_lshlrev_b32_e32 v28, 16, v103
	v_and_b32_e32 v29, 0xffff0000, v103
	v_lshlrev_b32_e32 v32, 16, v99
	v_and_b32_e32 v33, 0xffff0000, v99
	v_rcp_f32_e32 v18, v18
	v_rcp_f32_e32 v20, v20
	v_rcp_f32_e32 v21, v21
	v_rcp_f32_e32 v19, v19
	v_pk_mul_f32 v[12:13], v[12:13], s[56:57] op_sel_hi:[1,0]
	v_pk_mul_f32 v[10:11], v[10:11], s[56:57] op_sel_hi:[1,0]
	v_pk_mul_f32 v[26:27], v[26:27], v[30:31]
	v_pk_mul_f32 v[28:29], v[28:29], v[32:33]
	v_exp_f32_e32 v10, v10
	v_exp_f32_e32 v12, v12
	v_exp_f32_e32 v13, v13
	v_exp_f32_e32 v11, v11
	v_pk_mul_f32 v[24:25], v[24:25], v[28:29]
	v_pk_mul_f32 v[22:23], v[22:23], v[26:27]
	v_lshlrev_b32_e32 v26, 16, v104
	v_and_b32_e32 v27, 0xffff0000, v104
	v_lshlrev_b32_e32 v28, 16, v105
	v_and_b32_e32 v29, 0xffff0000, v105
	v_lshlrev_b32_e32 v30, 16, v100
	v_and_b32_e32 v31, 0xffff0000, v100
	v_lshlrev_b32_e32 v32, 16, v101
	v_and_b32_e32 v33, 0xffff0000, v101
	v_pk_mul_f32 v[26:27], v[26:27], v[30:31]
	v_pk_mul_f32 v[28:29], v[28:29], v[32:33]
	v_pk_add_f32 v[16:17], v[16:17], 1.0 op_sel_hi:[1,0]
	v_pk_add_f32 v[14:15], v[14:15], 1.0 op_sel_hi:[1,0]
	v_pk_add_f32 v[8:9], v[8:9], v[72:73]
	v_pk_add_f32 v[6:7], v[6:7], v[70:71]
	v_pk_mul_f32 v[28:29], v[20:21], v[28:29]
	v_pk_mul_f32 v[20:21], v[18:19], v[26:27]
	v_cvt_pk_bf16_f32 v18, v22, v23
	v_lshl_add_u64 v[22:23], s[74:75], 0, v[34:35]
	v_rcp_f32_e32 v14, v14
	v_rcp_f32_e32 v16, v16
	v_rcp_f32_e32 v17, v17
	v_rcp_f32_e32 v15, v15
	v_pk_mul_f32 v[8:9], v[8:9], s[56:57] op_sel_hi:[1,0]
	v_pk_mul_f32 v[6:7], v[6:7], s[56:57] op_sel_hi:[1,0]
	v_cvt_pk_bf16_f32 v19, v24, v25
	v_cvt_pk_bf16_f32 v20, v20, v21
	v_cvt_pk_bf16_f32 v21, v28, v29
	v_lshl_add_u64 v[22:23], v[22:23], 0, v[206:207]
	v_pk_add_f32 v[12:13], v[12:13], 1.0 op_sel_hi:[1,0]
	v_pk_add_f32 v[10:11], v[10:11], 1.0 op_sel_hi:[1,0]
	v_pk_add_f32 v[4:5], v[4:5], v[68:69]
	v_pk_add_f32 v[2:3], v[2:3], v[66:67]
	v_exp_f32_e32 v6, v6
	v_exp_f32_e32 v8, v8
	v_exp_f32_e32 v9, v9
	v_exp_f32_e32 v7, v7
	global_store_dwordx4 v[22:23], v[18:21], off
	s_waitcnt vmcnt(9)
	v_lshlrev_b32_e32 v22, 16, v95
	v_and_b32_e32 v23, 0xffff0000, v95
	v_lshlrev_b32_e32 v20, 16, v94
	v_and_b32_e32 v21, 0xffff0000, v94
	s_waitcnt vmcnt(8)
	v_lshlrev_b32_e32 v24, 16, v90
	v_and_b32_e32 v25, 0xffff0000, v90
	v_lshlrev_b32_e32 v26, 16, v91
	v_and_b32_e32 v27, 0xffff0000, v91
	v_rcp_f32_e32 v10, v10
	v_rcp_f32_e32 v12, v12
	v_rcp_f32_e32 v13, v13
	v_rcp_f32_e32 v11, v11
	v_pk_mul_f32 v[4:5], v[4:5], s[56:57] op_sel_hi:[1,0]
	v_pk_mul_f32 v[2:3], v[2:3], s[56:57] op_sel_hi:[1,0]
	v_pk_mul_f32 v[20:21], v[20:21], v[24:25]
	v_pk_mul_f32 v[22:23], v[22:23], v[26:27]
	v_exp_f32_e32 v2, v2
	v_exp_f32_e32 v4, v4
	v_exp_f32_e32 v5, v5
	v_exp_f32_e32 v3, v3
	v_pk_mul_f32 v[16:17], v[16:17], v[22:23]
	v_pk_mul_f32 v[14:15], v[14:15], v[20:21]
	v_lshlrev_b32_e32 v20, 16, v96
	v_and_b32_e32 v21, 0xffff0000, v96
	v_lshlrev_b32_e32 v22, 16, v97
	v_and_b32_e32 v23, 0xffff0000, v97
	v_lshlrev_b32_e32 v24, 16, v92
	v_and_b32_e32 v25, 0xffff0000, v92
	v_lshlrev_b32_e32 v26, 16, v93
	v_and_b32_e32 v27, 0xffff0000, v93
	v_lshlrev_b64 v[18:19], 7, v[134:135]
	v_pk_mul_f32 v[20:21], v[20:21], v[24:25]
	v_pk_mul_f32 v[22:23], v[22:23], v[26:27]
	v_pk_add_f32 v[8:9], v[8:9], 1.0 op_sel_hi:[1,0]
	v_pk_add_f32 v[6:7], v[6:7], 1.0 op_sel_hi:[1,0]
	v_pk_mul_f32 v[22:23], v[12:13], v[22:23]
	v_pk_mul_f32 v[12:13], v[10:11], v[20:21]
	v_cvt_pk_bf16_f32 v10, v14, v15
	v_lshl_add_u64 v[14:15], s[72:73], 0, v[18:19]
	v_rcp_f32_e32 v6, v6
	v_rcp_f32_e32 v8, v8
	v_rcp_f32_e32 v9, v9
	v_rcp_f32_e32 v7, v7
	v_cvt_pk_bf16_f32 v11, v16, v17
	v_cvt_pk_bf16_f32 v12, v12, v13
	v_cvt_pk_bf16_f32 v13, v22, v23
	v_lshl_add_u64 v[14:15], v[14:15], 0, v[206:207]
	v_pk_add_f32 v[4:5], v[4:5], 1.0 op_sel_hi:[1,0]
	v_pk_add_f32 v[2:3], v[2:3], 1.0 op_sel_hi:[1,0]
	global_store_dwordx4 v[14:15], v[10:13], off
	s_waitcnt vmcnt(7)
	v_lshlrev_b32_e32 v14, 16, v82
	v_and_b32_e32 v15, 0xffff0000, v82
	v_lshlrev_b32_e32 v10, 16, v86
	v_and_b32_e32 v11, 0xffff0000, v86
	v_lshlrev_b32_e32 v12, 16, v87
	v_and_b32_e32 v13, 0xffff0000, v87
	v_lshlrev_b32_e32 v16, 16, v83
	v_and_b32_e32 v17, 0xffff0000, v83
	v_rcp_f32_e32 v2, v2
	v_rcp_f32_e32 v4, v4
	v_rcp_f32_e32 v5, v5
	v_rcp_f32_e32 v3, v3
	v_pk_mul_f32 v[10:11], v[10:11], v[14:15]
	v_pk_mul_f32 v[12:13], v[12:13], v[16:17]
	v_pk_mul_f32 v[6:7], v[6:7], v[10:11]
	v_pk_mul_f32 v[8:9], v[8:9], v[12:13]
	v_lshlrev_b32_e32 v10, 16, v88
	v_and_b32_e32 v11, 0xffff0000, v88
	v_lshlrev_b32_e32 v12, 16, v89
	v_and_b32_e32 v13, 0xffff0000, v89
	v_lshlrev_b32_e32 v14, 16, v84
	v_and_b32_e32 v15, 0xffff0000, v84
	v_lshlrev_b32_e32 v16, 16, v85
	v_and_b32_e32 v17, 0xffff0000, v85
	v_pk_mul_f32 v[10:11], v[10:11], v[14:15]
	v_pk_mul_f32 v[12:13], v[12:13], v[16:17]
	v_readlane_b32 s84, v253, 15
	v_pk_mul_f32 v[12:13], v[4:5], v[12:13]
	v_pk_mul_f32 v[4:5], v[2:3], v[10:11]
	v_cvt_pk_bf16_f32 v2, v6, v7
	v_lshl_add_u64 v[6:7], s[74:75], 0, v[18:19]
	v_cvt_pk_bf16_f32 v3, v8, v9
	v_cvt_pk_bf16_f32 v4, v4, v5
	v_cvt_pk_bf16_f32 v5, v12, v13
	v_lshl_add_u64 v[6:7], v[6:7], 0, v[206:207]
	s_andn2_b64 vcc, exec, s[58:59]
	s_mov_b64 s[18:19], -1
	v_readlane_b32 s84, v253, 44
	v_readlane_b32 s78, v253, 9
	v_readlane_b32 s79, v253, 10
	v_readlane_b32 s80, v253, 11
	v_readlane_b32 s81, v253, 12
	v_readlane_b32 s82, v253, 13
	v_readlane_b32 s83, v253, 14
	v_readlane_b32 s85, v253, 16
	v_readlane_b32 s88, v253, 19
	v_readlane_b32 s89, v253, 20
	v_readlane_b32 s90, v253, 21
	v_readlane_b32 s91, v253, 22
	global_store_dwordx4 v[6:7], v[2:5], off
	s_cbranch_vccnz .LBB0_699
	s_andn2_b64 vcc, exec, s[20:21]
	s_cbranch_vccnz .LBB0_698
	s_barrier
	s_branch .LBB0_698

; #define G8_STA(bufoff, ptr, sg, h) G8_STAGE1(bufoff, (ptr) + (h) * ((sg) ? hA1 : hA0), ((sg) ? voffA1 : voffA0), ((sg) ? r64A1 : r64A0))
; #define G8_STB(bufoff, ptr, sg, h) G8_STAGE1(bufoff, (ptr) + (h) * ((sg) ? hB1 : hB0), ((sg) ? voffB1 : voffB0), ((sg) ? r64B1 : r64B0))
; #define G8_LDA(dst, b, h) do { _Pragma("unroll") for (int m = 0; m < 4; ++m) _Pragma("unroll") for (int k = 0; k < 2; ++k) dst[m][k] = *(const LAS bf16x8*)(lds + G8_SA(b, h) + aoff + m * 2048 + k * 1024); } while (0)
; #define G8_LDB(dst, b, h) do { _Pragma("unroll") for (int n = 0; n < 2; ++n) _Pragma("unroll") for (int k = 0; k < 2; ++k) dst[n][k] = *(const LAS bf16x8*)(lds + G8_SB(b, h) + boff + n * 2048 + k * 1024); } while (0)
; #define G8_MMA(ai, bj, At, Bt) do { __builtin_amdgcn_s_setprio(1); _Pragma("unroll") for (int m = 0; m < 4; ++m) _Pragma("unroll") for (int n = 0; n < 2; ++n) _Pragma("unroll") for (int k = 0; k < 2; ++k) \
;         acc[ai][bj][m][n] = __builtin_amdgcn_mfma_f32_16x16x32_bf16(Bt[n][k], At[m][k], acc[ai][bj][m][n], 0, 0, 0); __builtin_amdgcn_s_setprio(0); } while (0)
; #define G8_WAIT_V(n) asm volatile("s_waitcnt vmcnt(" #n ")" ::: "memory")
; #define G8_WAIT_L(n) asm volatile("s_waitcnt lgkmcnt(" #n ")" ::: "memory")
; #define G8_BAR __builtin_amdgcn_s_barrier()
; #define G8_SCHED __builtin_amdgcn_sched_barrier(0)
; template <class P>
; __device__ __forceinline__ void gemm_phase(LAS unsigned char* lds, const P& p, const int G, const int c) {
;     ...
;             G8_LDB(B0, 1, 0); G8_LDB(B1, 1, 1); G8_SCHED; G8_LDA(At, 1, 0); G8_STA(G8_SA(0, 1), a2, sg2, 1);
;             G8_WAIT_V(8); G8_WAIT_L(0); G8_BAR; G8_MMA(0, 0, At, B0); G8_MMA(0, 1, At, B1); G8_BAR; G8_SCHED;
;             G8_LDA(At, 1, 1); G8_STB(G8_SB(1, 0), b3, sg2, 0); G8_STB(G8_SB(1, 1), b3, sg2, 1); G8_STA(G8_SA(1, 0), a3, sg2, 0);
;             G8_WAIT_V(8); G8_WAIT_L(0); G8_BAR; G8_MMA(1, 0, At, B0); G8_MMA(1, 1, At, B1); G8_BAR; G8_SCHED;
.Lmid_770:
	s_barrier
	s_add_i32 s77, 0, 0x18000
	v_add_u32_e32 v161, s77, v156
	s_add_i32 s78, 0, 0x1c000
	ds_read_b128 v[130:133], v161
	ds_read_b128 v[134:137], v161 offset:1024
	ds_read_b128 v[138:141], v161 offset:2048
	ds_read_b128 v[162:165], v161 offset:3072
	v_add_u32_e32 v161, s78, v156
	ds_read_b128 v[166:169], v161
	ds_read_b128 v[170:173], v161 offset:1024
	ds_read_b128 v[174:177], v161 offset:2048
	ds_read_b128 v[178:181], v161 offset:3072
	s_mov_b32 m0, s33
	v_lshl_add_u64 v[206:207], v[154:155], 0, s[6:7]
	ds_read_b128 v[182:185], v160 offset:32768
	ds_read_b128 v[186:189], v160 offset:33792
	ds_read_b128 v[190:193], v160 offset:34816
	ds_read_b128 v[194:197], v160 offset:35840
	ds_read_b128 v[198:201], v160 offset:36864
	ds_read_b128 v[202:205], v160 offset:37888
	ds_read_b128 v[210:213], v160 offset:38912
	ds_read_b128 v[214:217], v160 offset:39936
	global_load_lds_dwordx4 v[206:207], off
	v_lshl_add_u64 v[206:207], v[154:155], 0, s[8:9]
	s_mov_b32 m0, s34
	s_nop 0
	global_load_lds_dwordx4 v[206:207], off
	s_waitcnt vmcnt(8)
	s_waitcnt lgkmcnt(0)
	s_barrier
	s_waitcnt lgkmcnt(0)
	v_mfma_f32_16x16x32_bf16 v[120:123], v[130:133], v[182:185], v[120:123]
	v_mfma_f32_16x16x32_bf16 v[124:127], v[138:141], v[182:185], v[124:127]
	v_mfma_f32_16x16x32_bf16 v[112:115], v[130:133], v[190:193], v[112:115]
	v_mfma_f32_16x16x32_bf16 v[116:119], v[138:141], v[190:193], v[116:119]
	v_mfma_f32_16x16x32_bf16 v[100:103], v[130:133], v[198:201], v[100:103]
	v_mfma_f32_16x16x32_bf16 v[108:111], v[138:141], v[198:201], v[108:111]
	v_mfma_f32_16x16x32_bf16 v[84:87], v[130:133], v[210:213], v[84:87]
	v_mfma_f32_16x16x32_bf16 v[72:75], v[138:141], v[210:213], v[72:75]
	v_mfma_f32_16x16x32_bf16 v[120:123], v[134:137], v[186:189], v[120:123]
	v_mfma_f32_16x16x32_bf16 v[124:127], v[162:165], v[186:189], v[124:127]
	v_mfma_f32_16x16x32_bf16 v[112:115], v[134:137], v[194:197], v[112:115]
	v_mfma_f32_16x16x32_bf16 v[116:119], v[162:165], v[194:197], v[116:119]
	v_mfma_f32_16x16x32_bf16 v[100:103], v[134:137], v[202:205], v[100:103]
	v_mfma_f32_16x16x32_bf16 v[108:111], v[162:165], v[202:205], v[108:111]
	v_mfma_f32_16x16x32_bf16 v[84:87], v[134:137], v[214:217], v[84:87]
	v_mfma_f32_16x16x32_bf16 v[72:75], v[162:165], v[214:217], v[72:75]
	v_mfma_f32_16x16x32_bf16 v[104:107], v[166:169], v[182:185], v[104:107]
	v_mfma_f32_16x16x32_bf16 v[92:95], v[174:177], v[182:185], v[92:95]
	v_mfma_f32_16x16x32_bf16 v[96:99], v[166:169], v[190:193], v[96:99]
	v_mfma_f32_16x16x32_bf16 v[80:83], v[174:177], v[190:193], v[80:83]
	v_mfma_f32_16x16x32_bf16 v[88:91], v[166:169], v[198:201], v[88:91]
	v_mfma_f32_16x16x32_bf16 v[76:79], v[174:177], v[198:201], v[76:79]
	v_mfma_f32_16x16x32_bf16 v[68:71], v[166:169], v[210:213], v[68:71]
	v_mfma_f32_16x16x32_bf16 v[64:67], v[174:177], v[210:213], v[64:67]
	v_mfma_f32_16x16x32_bf16 v[104:107], v[170:173], v[186:189], v[104:107]
	v_mfma_f32_16x16x32_bf16 v[92:95], v[178:181], v[186:189], v[92:95]
	v_mfma_f32_16x16x32_bf16 v[96:99], v[170:173], v[194:197], v[96:99]
	v_mfma_f32_16x16x32_bf16 v[80:83], v[178:181], v[194:197], v[80:83]
	v_mfma_f32_16x16x32_bf16 v[88:91], v[170:173], v[202:205], v[88:91]
	v_mfma_f32_16x16x32_bf16 v[76:79], v[178:181], v[202:205], v[76:79]
	v_mfma_f32_16x16x32_bf16 v[68:71], v[170:173], v[214:217], v[68:71]
	v_mfma_f32_16x16x32_bf16 v[64:67], v[178:181], v[214:217], v[64:67]
	s_barrier
	s_add_i32 s77, s77, s26
	v_lshl_add_u64 v[206:207], v[142:143], 0, s[12:13]
	s_mov_b32 m0, s77
	ds_read_b128 v[182:185], v160 offset:49152
	ds_read_b128 v[186:189], v160 offset:50176
	ds_read_b128 v[190:193], v160 offset:51200
	ds_read_b128 v[194:197], v160 offset:52224
	ds_read_b128 v[198:201], v160 offset:53248
	ds_read_b128 v[202:205], v160 offset:54272
	ds_read_b128 v[210:213], v160 offset:55296
	ds_read_b128 v[214:217], v160 offset:56320
	global_load_lds_dwordx4 v[206:207], off
	v_lshl_add_u64 v[206:207], v[142:143], 0, s[14:15]
	s_add_i32 m0, s77, 0x2000
	s_add_i32 s77, s78, s26
	global_load_lds_dwordx4 v[206:207], off
	v_lshl_add_u64 v[206:207], v[142:143], 0, s[22:23]
	s_mov_b32 m0, s77
	v_lshl_add_u64 v[142:143], v[142:143], 0, s[36:37]
	global_load_lds_dwordx4 v[206:207], off
	s_add_i32 m0, s77, 0x2000
	s_nop 0
	global_load_lds_dwordx4 v[142:143], off
	v_lshl_add_u64 v[142:143], v[154:155], 0, s[16:17]
	s_mov_b32 m0, s67
	s_nop 0
	global_load_lds_dwordx4 v[142:143], off
	v_lshl_add_u64 v[142:143], v[154:155], 0, s[20:21]
	s_mov_b32 m0, s69
	s_nop 0
	global_load_lds_dwordx4 v[142:143], off
	s_waitcnt vmcnt(8)
	s_waitcnt lgkmcnt(0)
	s_barrier
	s_waitcnt lgkmcnt(0)
	v_mfma_f32_16x16x32_bf16 v[60:63], v[130:133], v[182:185], v[60:63]
	v_mfma_f32_16x16x32_bf16 v[56:59], v[138:141], v[182:185], v[56:59]
	v_mfma_f32_16x16x32_bf16 v[52:55], v[130:133], v[190:193], v[52:55]
	v_mfma_f32_16x16x32_bf16 v[44:47], v[138:141], v[190:193], v[44:47]
	s_add_i32 s76, s76, 2
	v_mfma_f32_16x16x32_bf16 v[36:39], v[130:133], v[198:201], v[36:39]
	s_add_u32 s28, s28, 0x40000
	v_mfma_f32_16x16x32_bf16 v[28:31], v[138:141], v[198:201], v[28:31]
	s_addc_u32 s29, s29, 0
	v_mfma_f32_16x16x32_bf16 v[20:23], v[130:133], v[210:213], v[20:23]
	s_add_u32 s72, s72, 0x800000
	v_mfma_f32_16x16x32_bf16 v[12:15], v[138:141], v[210:213], v[12:15]
	s_addc_u32 s73, s73, 0
	v_mfma_f32_16x16x32_bf16 v[60:63], v[134:137], v[186:189], v[60:63]
	s_cmp_gt_u32 s76, 29
	v_mfma_f32_16x16x32_bf16 v[56:59], v[162:165], v[186:189], v[56:59]
	v_mfma_f32_16x16x32_bf16 v[52:55], v[134:137], v[194:197], v[52:55]
	v_mfma_f32_16x16x32_bf16 v[44:47], v[162:165], v[194:197], v[44:47]
	v_mfma_f32_16x16x32_bf16 v[36:39], v[134:137], v[202:205], v[36:39]
	v_mfma_f32_16x16x32_bf16 v[28:31], v[162:165], v[202:205], v[28:31]
	v_mfma_f32_16x16x32_bf16 v[20:23], v[134:137], v[214:217], v[20:23]
	v_mfma_f32_16x16x32_bf16 v[12:15], v[162:165], v[214:217], v[12:15]
	v_mfma_f32_16x16x32_bf16 v[48:51], v[166:169], v[182:185], v[48:51]
	v_mfma_f32_16x16x32_bf16 v[40:43], v[174:177], v[182:185], v[40:43]
	v_mfma_f32_16x16x32_bf16 v[32:35], v[166:169], v[190:193], v[32:35]
	v_mfma_f32_16x16x32_bf16 v[24:27], v[174:177], v[190:193], v[24:27]
	v_mfma_f32_16x16x32_bf16 v[16:19], v[166:169], v[198:201], v[16:19]
	v_mfma_f32_16x16x32_bf16 v[8:11], v[174:177], v[198:201], v[8:11]
	v_mfma_f32_16x16x32_bf16 v[4:7], v[166:169], v[210:213], v[4:7]
	v_mfma_f32_16x16x32_bf16 v[0:3], v[174:177], v[210:213], v[0:3]
	v_mfma_f32_16x16x32_bf16 v[48:51], v[170:173], v[186:189], v[48:51]
	v_mfma_f32_16x16x32_bf16 v[40:43], v[178:181], v[186:189], v[40:43]
	v_mfma_f32_16x16x32_bf16 v[32:35], v[170:173], v[194:197], v[32:35]
	v_mfma_f32_16x16x32_bf16 v[24:27], v[178:181], v[194:197], v[24:27]
	v_mfma_f32_16x16x32_bf16 v[16:19], v[170:173], v[202:205], v[16:19]
	v_mfma_f32_16x16x32_bf16 v[8:11], v[178:181], v[202:205], v[8:11]
	v_mfma_f32_16x16x32_bf16 v[4:7], v[170:173], v[214:217], v[4:7]
	v_mfma_f32_16x16x32_bf16 v[0:3], v[178:181], v[214:217], v[0:3]
	s_barrier
	s_cbranch_scc0 .LBB0_770
; #define LAS __attribute__((address_space(3)))
; #define G8_BAR __builtin_amdgcn_s_barrier()
; template <class P>
; __device__ __forceinline__ void gemm_phase(LAS unsigned char* lds, const P& p, const int G, const int c) {
;     ...
;         if (wr == 0) G8_BAR;
;         p.epi(acc, cur, wr, wc, fr, fq, lds);
;     __device__ __forceinline__ void epi(Acc& acc, const Unit& u, int wr, int wc, int fr, int fq, LAS unsigned char*) const {
;         const int rho = u.pm >> 6, col0 = u.pn * 256 + wc * 32 + 8 * fq;
;         f32x4 gt[2][2];
; #pragma unroll
;         for (int bj = 0; bj < 2; ++bj)
; #pragma unroll
;             for (int n = 0; n < 2; ++n) gt[bj][n] = *(const f32x4*)(mod + (3 + rho) * 3072 + 2048 + col0 + bj * 128 + n * 4);
; #pragma unroll
;         for (int ai = 0; ai < 2; ++ai)
; #pragma unroll
;             for (int m = 0; m < 4; ++m) { char* rowp = fo + ((((size_t)(u.pm * 4 + u.pn) * 256 + ai * 128 + wr * 64 + m * 16 + fr) * 256) + wc * 32 + 8 * fq) * 2;
.LBB0_773:
	s_lshr_b32 s18, s68, 6
	s_mulk_i32 s18, 0xc00
	s_addk_i32 s18, 0x2400
	s_ashr_i32 s19, s18, 31
	s_lshl_b64 s[18:19], s[18:19], 2
	v_readlane_b32 s28, v253, 24
	v_lshl_or_b32 v128, s75, 8, v157
	v_readlane_b32 s29, v253, 25
	s_add_u32 s18, s28, s18
	s_addc_u32 s19, s29, s19
	v_ashrrev_i32_e32 v129, 31, v128
	v_lshl_add_u64 v[132:133], v[128:129], 2, s[18:19]
	v_lshl_add_u64 v[134:135], v[132:133], 0, s[4:5]
	v_add_co_u32_e32 v132, vcc, s64, v132
	global_load_dwordx4 v[136:139], v[134:135], off offset:16
	global_load_dwordx4 v[128:131], v[134:135], off offset:512
	v_addc_co_u32_e32 v133, vcc, 0, v133, vcc
	global_load_dwordx4 v[140:143], v[132:133], off
	s_nop 0
	global_load_dwordx4 v[132:135], v[134:135], off offset:528
	s_lshl_b32 s18, s68, 2
	s_add_i32 s18, s18, s75
	s_ashr_i32 s19, s18, 31
	s_lshl_b64 s[18:19], s[18:19], 17
	v_lshl_add_u64 v[154:155], v[150:151], 0, s[18:19]
	v_lshl_add_u64 v[154:155], v[154:155], 0, v[148:149]
	v_add_co_u32_e32 v164, vcc, s64, v154
	v_lshl_add_u64 v[162:163], v[154:155], 0, s[4:5]
	s_nop 0
	v_addc_co_u32_e32 v165, vcc, 0, v155, vcc
	v_add_co_u32_e32 v168, vcc, s65, v154
	v_lshl_add_u64 v[166:167], v[154:155], 0, s[6:7]
	s_nop 0
	v_addc_co_u32_e32 v169, vcc, 0, v155, vcc
	v_lshl_add_u64 v[170:171], v[154:155], 0, s[8:9]
	s_mov_b32 s18, 0x10000
	s_cmp_lg_u64 s[38:39], 0
	s_cbranch_scc0 .Lalg_773
	s_barrier
; #define G8_BAR __builtin_amdgcn_s_barrier()
; template <class P>
; __device__ __forceinline__ void gemm_phase(LAS unsigned char* lds, const P& p, const int G, const int c) {
;     ...
;         if (!has_next) break;
; #pragma unroll
;         for (int a = 0; a < 2; ++a)
; #pragma unroll
;             for (int b = 0; b < 2; ++b)
; #pragma unroll
;                 for (int m = 0; m < 4; ++m)
; #pragma unroll
;                     for (int n = 0; n < 2; ++n) acc[a][b][m][n] = (f32x4){0.f, 0.f, 0.f, 0.f};
;         cur = nxt; ++ui; cA0 = nA0; cA1 = nA1; cB0 = nB0; cB1 = nB1;
;         if (wr == 1) G8_BAR;
;     __device__ __forceinline__ void epi(Acc& acc, const Unit& u, int wr, int wc, int fr, int fq, LAS unsigned char*) const {
;     ...
; #pragma unroll
;         for (int ai = 0; ai < 2; ++ai)
; #pragma unroll
;             for (int m = 0; m < 4; ++m) { char* rowp = fo + ((((size_t)(u.pm * 4 + u.pn) * 256 + ai * 128 + wr * 64 + m * 16 + fr) * 256) + wc * 32 + 8 * fq) * 2;
; #pragma unroll
;                 for (int bj = 0; bj < 2; ++bj) { const f32x4 v0 = gt[bj][0] * acc[ai][bj][m][0], v1 = gt[bj][1] * acc[ai][bj][m][1];
;                     u32x4 w; w.x = pk2(v0[0], v0[1]); w.y = pk2(v0[2], v0[3]); w.z = pk2(v1[0], v1[1]); w.w = pk2(v1[2], v1[3]);
;                     *(u32x4*)(rowp + bj * 256) = w; } }
.Lalg_773:
	s_waitcnt vmcnt(0)
	v_pk_mul_f32 v[126:127], v[126:127], v[138:139]
	v_pk_mul_f32 v[124:125], v[124:125], v[136:137]
	v_pk_mul_f32 v[106:107], v[106:107], v[130:131]
	v_pk_mul_f32 v[104:105], v[104:105], v[128:129]
	v_pk_mul_f32 v[98:99], v[98:99], v[130:131]
	v_pk_mul_f32 v[110:111], v[110:111], v[138:139]
	v_pk_mul_f32 v[108:109], v[108:109], v[136:137]
	v_pk_mul_f32 v[174:175], v[90:91], v[130:131]
	v_pk_mul_f32 v[176:177], v[88:89], v[128:129]
	v_pk_mul_f32 v[122:123], v[122:123], v[142:143]
	v_pk_mul_f32 v[120:121], v[120:121], v[140:141]
	v_pk_mul_f32 v[118:119], v[118:119], v[138:139]
	v_pk_mul_f32 v[116:117], v[116:117], v[136:137]
	v_pk_mul_f32 v[172:173], v[96:97], v[128:129]
	v_cvt_pk_bf16_f32 v88, v124, v125
	v_cvt_pk_bf16_f32 v89, v126, v127
	v_pk_mul_f32 v[94:95], v[94:95], v[134:135]
	v_pk_mul_f32 v[92:93], v[92:93], v[132:133]
	v_cvt_pk_bf16_f32 v90, v104, v105
	v_cvt_pk_bf16_f32 v91, v106, v107
	v_pk_mul_f32 v[104:105], v[114:115], v[142:143]
	v_pk_mul_f32 v[106:107], v[112:113], v[140:141]
	v_pk_mul_f32 v[112:113], v[82:83], v[134:135]
	v_pk_mul_f32 v[82:83], v[80:81], v[132:133]
	v_cvt_pk_bf16_f32 v81, v98, v99
	v_pk_mul_f32 v[102:103], v[102:103], v[142:143]
	v_pk_mul_f32 v[98:99], v[100:101], v[140:141]
	v_cvt_pk_bf16_f32 v100, v108, v109
	v_cvt_pk_bf16_f32 v101, v110, v111
	v_pk_mul_f32 v[108:109], v[78:79], v[134:135]
	v_pk_mul_f32 v[78:79], v[76:77], v[132:133]
	v_cvt_pk_bf16_f32 v76, v176, v177
	v_cvt_pk_bf16_f32 v77, v174, v175
	v_pk_mul_f32 v[110:111], v[86:87], v[142:143]
	v_cvt_pk_bf16_f32 v86, v120, v121
	v_cvt_pk_bf16_f32 v87, v122, v123
	v_cvt_pk_bf16_f32 v96, v116, v117
	v_cvt_pk_bf16_f32 v97, v118, v119
	v_cvt_pk_bf16_f32 v80, v172, v173
	v_cvt_pk_bf16_f32 v92, v92, v93
	v_cvt_pk_bf16_f32 v93, v94, v95
	v_cvt_pk_bf16_f32 v94, v106, v107
	v_cvt_pk_bf16_f32 v95, v104, v105
	v_cvt_pk_bf16_f32 v82, v82, v83
	v_cvt_pk_bf16_f32 v83, v112, v113
	v_cvt_pk_bf16_f32 v98, v98, v99
	v_cvt_pk_bf16_f32 v99, v102, v103
	v_cvt_pk_bf16_f32 v78, v78, v79
	v_cvt_pk_bf16_f32 v79, v108, v109
	global_store_dwordx4 v[154:155], v[86:89], off
	global_store_dwordx4 v[154:155], v[90:93], off offset:256
	global_store_dwordx4 v[164:165], v[94:97], off
	global_store_dwordx4 v[162:163], v[80:83], off offset:256
	global_store_dwordx4 v[168:169], v[98:101], off
	global_store_dwordx4 v[166:167], v[76:79], off offset:256
	v_pk_mul_f32 v[84:85], v[84:85], v[140:141]
	v_pk_mul_f32 v[70:71], v[70:71], v[130:131]
	v_pk_mul_f32 v[76:77], v[74:75], v[138:139]
	v_pk_mul_f32 v[74:75], v[72:73], v[136:137]
	v_cvt_pk_bf16_f32 v72, v84, v85
	v_cvt_pk_bf16_f32 v74, v74, v75
	v_cvt_pk_bf16_f32 v75, v76, v77
	v_add_co_u32_e32 v76, vcc, s66, v154
	v_cvt_pk_bf16_f32 v73, v110, v111
	s_nop 0
	v_addc_co_u32_e32 v77, vcc, 0, v155, vcc
	global_store_dwordx4 v[76:77], v[72:75], off
	v_pk_mul_f32 v[68:69], v[68:69], v[128:129]
	v_pk_mul_f32 v[60:61], v[60:61], v[140:141]
	v_pk_mul_f32 v[72:73], v[66:67], v[134:135]
	v_pk_mul_f32 v[66:67], v[64:65], v[132:133]
	v_cvt_pk_bf16_f32 v64, v68, v69
	v_cvt_pk_bf16_f32 v65, v70, v71
	v_cvt_pk_bf16_f32 v66, v66, v67
	v_cvt_pk_bf16_f32 v67, v72, v73
	global_store_dwordx4 v[170:171], v[64:67], off offset:256
	v_pk_mul_f32 v[62:63], v[62:63], v[142:143]
	v_pk_mul_f32 v[50:51], v[50:51], v[130:131]
	v_pk_mul_f32 v[66:67], v[58:59], v[138:139]
	v_pk_mul_f32 v[58:59], v[56:57], v[136:137]
	v_cvt_pk_bf16_f32 v56, v60, v61
	v_add_co_u32_e32 v60, vcc, s18, v154
	v_cvt_pk_bf16_f32 v57, v62, v63
	v_cvt_pk_bf16_f32 v58, v58, v59
	v_cvt_pk_bf16_f32 v59, v66, v67
	v_addc_co_u32_e32 v61, vcc, 0, v155, vcc
	global_store_dwordx4 v[60:61], v[56:59], off
	v_pk_mul_f32 v[48:49], v[48:49], v[128:129]
	v_lshl_add_u64 v[64:65], v[154:155], 0, s[44:45]
	v_pk_mul_f32 v[56:57], v[42:43], v[134:135]
	v_pk_mul_f32 v[42:43], v[40:41], v[132:133]
	v_cvt_pk_bf16_f32 v40, v48, v49
	v_cvt_pk_bf16_f32 v41, v50, v51
	v_cvt_pk_bf16_f32 v42, v42, v43
	v_cvt_pk_bf16_f32 v43, v56, v57
	global_store_dwordx4 v[64:65], v[40:43], off offset:256
	v_pk_mul_f32 v[44:45], v[44:45], v[136:137]
	s_mov_b32 s18, 0x12000
	v_pk_mul_f32 v[42:43], v[54:55], v[142:143]
	v_pk_mul_f32 v[40:41], v[52:53], v[140:141]
	v_pk_mul_f32 v[46:47], v[46:47], v[138:139]
	v_cvt_pk_bf16_f32 v40, v40, v41
	v_cvt_pk_bf16_f32 v41, v42, v43
	v_cvt_pk_bf16_f32 v42, v44, v45
	v_add_co_u32_e32 v44, vcc, s18, v154
	v_cvt_pk_bf16_f32 v43, v46, v47
	s_nop 0
	v_addc_co_u32_e32 v45, vcc, 0, v155, vcc
	global_store_dwordx4 v[44:45], v[40:43], off
	v_pk_mul_f32 v[34:35], v[34:35], v[130:131]
	v_pk_mul_f32 v[32:33], v[32:33], v[128:129]
	v_pk_mul_f32 v[40:41], v[26:27], v[134:135]
	v_pk_mul_f32 v[26:27], v[24:25], v[132:133]
	v_lshl_add_u64 v[48:49], v[154:155], 0, s[46:47]
	v_cvt_pk_bf16_f32 v24, v32, v33
	v_cvt_pk_bf16_f32 v25, v34, v35
	v_cvt_pk_bf16_f32 v26, v26, v27
	v_cvt_pk_bf16_f32 v27, v40, v41
	global_store_dwordx4 v[48:49], v[24:27], off offset:256
	v_pk_mul_f32 v[28:29], v[28:29], v[136:137]
	v_pk_mul_f32 v[30:31], v[30:31], v[138:139]
	v_pk_mul_f32 v[26:27], v[38:39], v[142:143]
	v_pk_mul_f32 v[24:25], v[36:37], v[140:141]
	v_pk_mul_f32 v[18:19], v[18:19], v[130:131]
	v_cvt_pk_bf16_f32 v24, v24, v25
	v_cvt_pk_bf16_f32 v25, v26, v27
	v_cvt_pk_bf16_f32 v26, v28, v29
	v_add_co_u32_e32 v28, vcc, s50, v154
	v_cvt_pk_bf16_f32 v27, v30, v31
	s_nop 0
	v_addc_co_u32_e32 v29, vcc, 0, v155, vcc
	global_store_dwordx4 v[28:29], v[24:27], off
	v_pk_mul_f32 v[16:17], v[16:17], v[128:129]
	v_lshl_add_u64 v[32:33], v[154:155], 0, s[48:49]
	v_pk_mul_f32 v[24:25], v[10:11], v[134:135]
	v_pk_mul_f32 v[10:11], v[8:9], v[132:133]
	v_cvt_pk_bf16_f32 v8, v16, v17
	v_cvt_pk_bf16_f32 v9, v18, v19
	v_cvt_pk_bf16_f32 v10, v10, v11
	v_cvt_pk_bf16_f32 v11, v24, v25
	global_store_dwordx4 v[32:33], v[8:11], off offset:256
	v_pk_mul_f32 v[12:13], v[12:13], v[136:137]
	v_pk_mul_f32 v[14:15], v[14:15], v[138:139]
	v_pk_mul_f32 v[10:11], v[22:23], v[142:143]
	v_pk_mul_f32 v[8:9], v[20:21], v[140:141]
	v_pk_mul_f32 v[6:7], v[6:7], v[130:131]
	v_cvt_pk_bf16_f32 v8, v8, v9
	v_cvt_pk_bf16_f32 v9, v10, v11
	v_cvt_pk_bf16_f32 v10, v12, v13
	v_add_co_u32_e32 v12, vcc, s51, v154
	v_cvt_pk_bf16_f32 v11, v14, v15
	s_nop 0
	v_addc_co_u32_e32 v13, vcc, 0, v155, vcc
	global_store_dwordx4 v[12:13], v[8:11], off
	v_pk_mul_f32 v[4:5], v[4:5], v[128:129]
	v_lshl_add_u64 v[16:17], v[154:155], 0, s[52:53]
	v_pk_mul_f32 v[8:9], v[2:3], v[134:135]
	v_pk_mul_f32 v[2:3], v[0:1], v[132:133]
	v_cvt_pk_bf16_f32 v0, v4, v5
	v_cvt_pk_bf16_f32 v1, v6, v7
	v_cvt_pk_bf16_f32 v2, v2, v3
	v_cvt_pk_bf16_f32 v3, v8, v9
	s_andn2_b64 vcc, exec, s[54:55]
	s_mov_b64 s[18:19], -1
	global_store_dwordx4 v[16:17], v[0:3], off offset:256
	s_cbranch_vccnz .LBB0_762
	s_andn2_b64 vcc, exec, s[10:11]
	s_cbranch_vccnz .LBB0_761
	s_barrier
	s_branch .LBB0_761
